# prompt attention main loop: K fragments for QK^T through three rotating register quads (reads issued 3 MFMAs ahead instead of in wait-bound pairs); lane constants v200/v201/v214/v215/v216 borrowed and
# baseline (speedup 1.0000x reference)
; #define SBAR() __builtin_amdgcn_sched_barrier(0)
; #define VMW() asm volatile("s_waitcnt vmcnt(0)" ::: "memory")
; #define SLOAD_H(Kp, Vp, Cp, k0) do { S.st_b0 = (Cp)[(unsigned)((k0) + sr + 32 * (tid & 1))]; S.st_v0 = load8<TIn>(ROW(Vp, k0, sr)); S.st_v1 = load8<TIn>(ROW(Vp, k0, 32 + sr));              \
;                          S.st_k0 = load8<TIn>(ROW(Kp, k0, sr)); S.st_k1 = load8<TIn>(ROW(Kp, k0, 32 + sr)); } while (0)
; #define SWRITE_HK(bf) do { B_lds[(bf) * 64 + sr + 32 * (tid & 1)] = S.st_b0; *(bf16x8*)(K_lds + (bf) * SHM_K + kws) = S.st_k0; *(bf16x8*)(K_lds + (bf) * SHM_K + kws + 32 * 256) = S.st_k1; } while (0)
; template <class TIn, class TOut>
; __device__ __forceinline__ void causal_swa_prime(const BlockRef<TIn, TOut>& cur, int W, char* lds, Seam<TIn>& S) {
;     constexpr bool F32 = same_t<TIn, float>::v;
;     const int tid = otid(), wid = __builtin_amdgcn_readfirstlane(tid >> 6), lane = tid & 63, r32 = lane & 31, hi = lane >> 5;
;     const int sr = tid >> 4, sc = (tid & 15) * 8, kws = KSWZ(sr, sc * 2); char* K_lds = lds + 2 * SHM_V; float* B_lds = (float*)(lds + 2 * SHM_V + 2 * SHM_K + NW * 64 * 4);
;     const int kb0 = swa_jlo(cur.P0, W) * KVBLK;
;     for (int d0 = 0; d0 < 8; ++d0) S.qr[d0] = load8<TIn>(cur.Q + (unsigned)((wid * QBLK + r32) * PITCH + d0 * 16 + hi * 8));
;     if constexpr (F32) { SLOAD_F((const float*)cur.K, kb0); VMW(); SWRITE_KF(0); SBAR(); SLOAD_F((const float*)cur.V, kb0); }
;     else { SLOAD_H(cur.K, cur.V, cur.CB, kb0); VMW(); SWRITE_HK(0); }
;     __syncthreads();
;     ...
;     const T* Q = (const T*)(a.p->ws + WS_R0); const T* K = (const T*)(a.p->ws + WS_R0 + RSZ); const T* V = (const T*)(a.p->ws + WS_R0 + 2 * RSZ); const T* Z = (const T*)(a.p->ws + WS_R0 + 3 * RSZ); T* O = (T*)(a.p->ws + (mode == 1 ? WS_DUMMY : WS_R0));
;     const float* CB = (const float*)(a.p->ws + WS_CBP);
;     char* lds = (char*)ldsb;
;     constexpr int nqb = SEQ / QB, nx = nqb / 2, total = nx * NBH;
;     const int stride = gridDim.x;
;     int L = (gridDim.x == 256) ? (int)((blockIdx.x & 7) * 32 + (blockIdx.x >> 3)) : (int)blockIdx.x;
;     if (mode == 2) L = total;
;     if (L < total) {
;     ...
;         BlockRef<T, T> cur, nxt; int pass = 0;
;         MKREF(cur, L, 0);
;         Seam<T> S;
;         causal_swa_prime<T, T>(cur, SEQ, lds, S);
.LBB0_1232:
	s_or_b64 exec, exec, s[2:3]
	s_mov_b64 s[8:9], s[50:51]
	s_waitcnt lgkmcnt(0)
	s_barrier
	s_load_dwordx2 s[6:7], s[8:9], 0xa8
	v_readlane_b32 s2, v254, 12
	v_readlane_b32 s3, v254, 13
	s_waitcnt lgkmcnt(0)
	s_add_u32 s10, s6, 0xf000000
	s_addc_u32 s11, s7, 0
	s_add_u32 s12, s6, 0x27300000
	s_addc_u32 s13, s7, 0
	s_andn2_b64 vcc, exec, s[2:3]
	s_cbranch_vccnz .LBB0_1413
	v_mov_b32_e32 v200, 0xff800000
	s_add_u32 s0, s6, 0x17100000
	s_addc_u32 s46, s7, 0
	s_add_u32 s47, s6, 0x1f200000
	s_addc_u32 s48, s7, 0
	s_add_u32 s49, s6, 0xec00000
	s_addc_u32 s50, s7, 0
	v_readlane_b32 s2, v254, 60
	v_readlane_b32 s3, v254, 61
	s_add_u32 s36, s10, s2
	s_addc_u32 s37, s11, s3
	s_add_u32 s54, s12, s2
	s_addc_u32 s55, s13, s3
	v_readlane_b32 s2, v254, 62
	s_mov_b32 s40, s62
	v_readlane_b32 s3, v254, 63
	s_add_u32 s62, s0, s2
	s_addc_u32 s63, s46, s3
	s_add_u32 s64, s47, s2
	s_addc_u32 s65, s48, s3
	v_readlane_b32 s2, v254, 15
	v_readlane_b32 s3, v254, 16
	s_add_u32 s66, s49, s2
	s_getreg_b32 s2, hwreg(HW_REG_HW_ID, 0, 6)
	s_addc_u32 s67, s50, s3
	s_and_b32 s2, s2, 63
	s_lshl_b32 s2, s2, 2
	s_add_i32 s2, s2, 0
	s_add_i32 s2, s2, 0x23e00
	v_mov_b32_e32 v0, s2
	ds_read_b32 v0, v0
	v_mbcnt_lo_u32_b32 v4, -1, 0
	v_readlane_b32 s57, v254, 17
	v_mbcnt_hi_u32_b32 v4, -1, v4
	s_mov_b32 s51, 0
	s_waitcnt lgkmcnt(0)
	v_readfirstlane_b32 s2, v0
	v_lshrrev_b32_e32 v2, 2, v4
	v_and_b32_e32 v2, 8, v2
	v_lshl_add_u32 v12, s2, 6, v4
	v_ashrrev_i32_e32 v13, 4, v12
	v_readfirstlane_b32 s2, v12
	s_lshr_b32 s2, s2, 1
	s_and_b32 s2, s2, 0x1fffe0
	v_and_or_b32 v0, v4, 31, s2
	v_lshl_or_b32 v0, v0, 11, v2
	v_lshl_add_u64 v[2:3], v[0:1], 1, s[36:37]
	v_lshlrev_b32_e32 v0, 3, v4
	v_and_b32_e32 v14, 0x78, v0
	v_readlane_b32 s2, v254, 18
	v_lshlrev_b32_e32 v0, 5, v4
	v_and_b32_e32 v15, 32, v0
	v_add_u32_e32 v6, s2, v13
	v_add_u32_e32 v0, v6, v15
	v_lshl_add_u64 v[4:5], v[0:1], 2, s[66:67]
	v_lshl_or_b32 v0, v6, 11, v14
	global_load_dwordx4 v[172:175], v[2:3], off
	global_load_dwordx4 v[168:171], v[2:3], off offset:32
	global_load_dwordx4 v[164:167], v[2:3], off offset:64
	global_load_dwordx4 v[160:163], v[2:3], off offset:96
	global_load_dword v176, v[4:5], off
	v_lshlrev_b64 v[4:5], 1, v[0:1]
	v_add_u32_e32 v0, 0x10000, v0
	v_lshlrev_b64 v[6:7], 1, v[0:1]
	v_lshl_add_u64 v[8:9], s[64:65], 0, v[6:7]
	v_lshl_add_u64 v[6:7], s[62:63], 0, v[6:7]
	v_lshl_add_u64 v[10:11], s[62:63], 0, v[4:5]
	global_load_dwordx4 v[112:115], v[8:9], off
	global_load_dwordx4 v[116:119], v[10:11], off
	global_load_dwordx4 v[120:123], v[6:7], off
	global_load_dwordx4 v[156:159], v[2:3], off offset:128
	global_load_dwordx4 v[152:155], v[2:3], off offset:160
	global_load_dwordx4 v[148:151], v[2:3], off offset:192
	global_load_dwordx4 v[144:147], v[2:3], off offset:224
	v_lshl_add_u64 v[2:3], s[64:65], 0, v[4:5]
	global_load_dwordx4 v[124:127], v[2:3], off
	v_lshlrev_b32_e32 v0, 1, v14
	s_movk_i32 s2, 0x70
	s_waitcnt vmcnt(0)
	v_lshlrev_b32_e32 v2, 2, v15
	v_bitop3_b32 v0, v0, v12, s2 bitop3:0x78
	v_lshlrev_b32_e32 v4, 2, v13
	v_readlane_b32 s2, v255, 3
	v_readlane_b32 s52, v254, 14
	s_mov_b32 s53, s57
	s_mov_b64 s[14:15], s[36:37]
	s_mov_b64 s[16:17], s[54:55]
	s_mov_b64 s[18:19], s[64:65]
	s_mov_b64 s[24:25], s[66:67]
	v_lshlrev_b32_e32 v3, 8, v13
	v_add3_u32 v2, s2, v4, v2
	s_mov_b64 s[26:27], s[62:63]
	v_add3_u32 v0, 0, v3, v0
	s_waitcnt vmcnt(8)
	ds_write_b32 v2, v176
	s_waitcnt vmcnt(6)
	ds_write_b128 v0, v[116:119] offset:32768
	s_waitcnt vmcnt(5)
	ds_write_b128 v0, v[120:123] offset:40960
	s_waitcnt lgkmcnt(0)
	s_barrier
	s_branch .LBB0_1235

; #define SBAR() __builtin_amdgcn_sched_barrier(0)
; #define VMW() asm volatile("s_waitcnt vmcnt(0)" ::: "memory")
; template <int KB, bool SK>
; __device__ __forceinline__ void qkt(f32x16& p0, f32x16& p1, const char* K_lds, const float* B_lds, int r32, int hi, const bf16x8* qr, bool act) {
;     if (SK && !act) { const float NEG = -__builtin_inff();
; #pragma unroll
;         for (int r = 0; r < 16; ++r) { p0[r] = NEG; p1[r] = NEG; } return; }
;     ...
;     p0 = f32x16{}; p1 = f32x16{};
;     ...
;     p0 = *(const f32x16*)(B_lds + KB * 64 + hi * 32); p1 = *(const f32x16*)(B_lds + KB * 64 + hi * 32 + 16);
;     ...
;     const char* kb[4];
; #pragma unroll
;     for (int dd = 0; dd < 4; ++dd) kb[dd] = K_lds + KB * SHM_K + KSWZ(r32, (dd * 16 + hi * 8) * 2);
; #pragma unroll
;     for (int d0 = 0; d0 < 8; ++d0) { const char* a = kb[d0 & 3] + (d0 >> 2) * 128;
;         bf16x8 b0 = *reinterpret_cast<const bf16x8*>(a);
;         bf16x8 b1 = *reinterpret_cast<const bf16x8*>(a + 32 * 256);
;         p0 = __builtin_amdgcn_mfma_f32_32x32x16_bf16(b0, qr[d0], p0, 0, 0, 0);
;         p1 = __builtin_amdgcn_mfma_f32_32x32x16_bf16(b1, qr[d0], p1, 0, 0, 0); }
; }
; template <class TIn, class TOut>
; __device__ __forceinline__ void causal_swa_block(const BlockRef<TIn, TOut>& cur, const BlockRef<TIn, TOut>& nxt, int skv, int W, char* lds, Seam<TIn>& S) {
;     ...
;     const int qlo = cur.P0 + wid * QBLK, qm = qlo + r32 - 4 * hi;
;     char* V_lds = lds; char* K_lds = lds + 2 * SHM_V; float* B_lds = (float*)(lds + 2 * SHM_V + 2 * SHM_K + NW * 64 * 4);
;     float* ws = (float*)(lds + 2 * SHM_V + 2 * SHM_K) + wid * 64; float* li_l = ws, * al_l = ws + 32;
;     float m_reg = -1e30f, l_reg = 0; f32x16 o[4] = {};
;     const int sr = tid >> 4, sc = (tid & 15) * 8, vst0 = v_st(sr, sc), vst1 = v_st(32 + sr, sc), kws = KSWZ(sr, sc * 2);
;     const int vb0 = (int)(uintptr_t)V_lds + v_rd_base(lane);
;     const TIn* Kh = cur.K; const TIn* Vh = cur.V; const float* Ch = cur.CB;
;     ...
;     constexpr int NQL = F32 ? 16 : 8;
;     constexpr bool SK = WSKIP && !F32;
;     ...
;     f32x16 pA0, pA1, pB0, pB1; float mnA, mnB, alA, alB; bf16x8 pa0, pa1, pa2, pa3;
;     if constexpr (F32) { VMW(); SWRITE_VF(0); SBAR(); } else { SWRITE_HV(0); SBAR(); }
;     if (NT > 1) { if constexpr (F32) SLOAD_F((const float*)Kh, KBASE(1)); else SLOAD_H(Kh, Vh, Ch, KBASE(1)); }
;     SBAR(); qkt<0, SK>(pA0, pA1, K_lds, B_lds, r32, hi, S.qr, ACT(0));
.LBB0_1239:
	v_bfe_u32 v221, v218, 5, 1
	s_ashr_i32 s2, s29, 1
	v_and_b32_e32 v220, 31, v218
	s_and_b32 s60, s2, 0xffffffe0
	v_lshlrev_b32_e32 v0, 2, v221
	s_add_i32 s57, s60, s57
	v_sub_u32_e32 v2, v220, v0
	v_add_u32_e32 v201, s57, v2
	v_lshlrev_b32_e32 v38, 4, v218
	v_lshlrev_b32_e32 v37, 4, v221
	v_and_b32_e32 v38, 0x70, v38
	v_lshlrev_b32_e32 v36, 8, v220
	v_xad_u32 v39, v37, v38, 0
	v_add_u32_e32 v235, v39, v36
	v_or_b32_e32 v39, 32, v37
	v_lshlrev_b32_e32 v2, 7, v221
	v_xad_u32 v39, v39, v38, 0
	v_add_u32_e32 v236, 0, v2
	v_add_u32_e32 v234, v39, v36
	v_or_b32_e32 v39, 64, v37
	v_or_b32_e32 v37, 0x60, v37
	v_add_u32_e32 v239, 0x10800, v236
	v_xad_u32 v39, v39, v38, 0
	v_xad_u32 v37, v37, v38, 0
	ds_read_b128 v[18:21], v239
	ds_read_b128 v[22:25], v239 offset:16
	ds_read_b128 v[26:29], v239 offset:32
	ds_read_b128 v[30:33], v239 offset:48
	ds_read_b128 v[14:17], v239 offset:112
	ds_read_b128 v[10:13], v239 offset:96
	ds_read_b128 v[6:9], v239 offset:80
	ds_read_b128 v[2:5], v239 offset:64
	v_add_u32_e32 v233, v39, v36
	v_add_u32_e32 v232, v37, v36
	ds_read_b128 v[36:39], v235 offset:32768
	ds_read_b128 v[40:43], v235 offset:40960
	s_waitcnt lgkmcnt(1)
	v_mfma_f32_32x32x16_bf16 v[18:33], v[36:39], v[172:175], v[18:33]
	s_or_b32 s2, s68, 63
	s_cmp_le_i32 s2, s57
	s_cselect_b64 s[2:3], -1, 0
	s_add_i32 s58, s57, 0xfffff01f
	s_cmp_gt_i32 s68, s58
	s_cselect_b64 s[72:73], -1, 0
	s_and_b64 s[2:3], s[2:3], s[72:73]
	s_waitcnt lgkmcnt(0)
	v_mfma_f32_32x32x16_bf16 v[2:17], v[40:43], v[172:175], v[2:17]
	ds_read_b128 v[36:39], v234 offset:32768
	ds_read_b128 v[40:43], v234 offset:40960
	s_and_b64 vcc, exec, s[2:3]
	s_waitcnt lgkmcnt(1)
	v_mfma_f32_32x32x16_bf16 v[18:33], v[36:39], v[168:171], v[18:33]
	s_waitcnt lgkmcnt(0)
	v_mfma_f32_32x32x16_bf16 v[2:17], v[40:43], v[168:171], v[2:17]
	ds_read_b128 v[36:39], v233 offset:32768
	ds_read_b128 v[40:43], v233 offset:40960
	s_waitcnt lgkmcnt(1)
	v_mfma_f32_32x32x16_bf16 v[18:33], v[36:39], v[164:167], v[18:33]
	s_waitcnt lgkmcnt(0)
	v_mfma_f32_32x32x16_bf16 v[2:17], v[40:43], v[164:167], v[2:17]
	ds_read_b128 v[36:39], v232 offset:32768
	ds_read_b128 v[40:43], v232 offset:40960
	s_waitcnt lgkmcnt(1)
	v_mfma_f32_32x32x16_bf16 v[18:33], v[36:39], v[160:163], v[18:33]
	s_waitcnt lgkmcnt(0)
	v_mfma_f32_32x32x16_bf16 v[2:17], v[40:43], v[160:163], v[2:17]
	ds_read_b128 v[36:39], v235 offset:32896
	ds_read_b128 v[40:43], v235 offset:41088
	s_waitcnt lgkmcnt(1)
	v_mfma_f32_32x32x16_bf16 v[18:33], v[36:39], v[156:159], v[18:33]
	s_waitcnt lgkmcnt(0)
	v_mfma_f32_32x32x16_bf16 v[2:17], v[40:43], v[156:159], v[2:17]
	ds_read_b128 v[36:39], v234 offset:32896
	ds_read_b128 v[40:43], v234 offset:41088
	s_waitcnt lgkmcnt(1)
	v_mfma_f32_32x32x16_bf16 v[18:33], v[36:39], v[152:155], v[18:33]
	s_waitcnt lgkmcnt(0)
	v_mfma_f32_32x32x16_bf16 v[2:17], v[40:43], v[152:155], v[2:17]
	ds_read_b128 v[36:39], v233 offset:32896
	ds_read_b128 v[40:43], v233 offset:41088
	s_waitcnt lgkmcnt(1)
	v_mfma_f32_32x32x16_bf16 v[18:33], v[36:39], v[148:151], v[18:33]
	s_waitcnt lgkmcnt(0)
	v_mfma_f32_32x32x16_bf16 v[2:17], v[40:43], v[148:151], v[2:17]
	ds_read_b128 v[36:39], v232 offset:32896
	ds_read_b128 v[40:43], v232 offset:41088
	s_waitcnt lgkmcnt(1)
	v_mfma_f32_32x32x16_bf16 v[18:33], v[36:39], v[144:147], v[18:33]
	s_waitcnt lgkmcnt(0)
	v_mfma_f32_32x32x16_bf16 v[2:17], v[40:43], v[144:147], v[2:17]
	s_cbranch_vccnz .LBB0_1241
; __device__ __forceinline__ void mask_tile(f32x16& p0, f32x16& p1, int dq, unsigned W) {
;     const float NEG = -__builtin_inff();
; #pragma unroll
;     for (int r = 0; r < 16; ++r) {
;         const int c = (r & 3) + 8 * (r >> 2);
;         if ((unsigned)(dq - c) >= W) p0[r] = NEG;
;         if ((unsigned)(dq - c - 32) >= W) p1[r] = NEG;
;     }
; }
	v_subrev_u32_e32 v36, s68, v201
	v_cmp_gt_u32_e32 vcc, s81, v36
	v_add_u32_e32 v37, 0xffffefe0, v36
	s_nop 5
	v_cndmask_b32_e32 v18, v200, v18, vcc
	v_cmp_lt_u32_e32 vcc, s82, v37
	v_add_u32_e32 v37, 0xffffefff, v36
	s_nop 0
	v_cndmask_b32_e32 v2, v200, v2, vcc
	v_cmp_lt_u32_e32 vcc, s82, v37
	v_add_u32_e32 v37, 0xffffefdf, v36
	s_nop 0
	v_cndmask_b32_e32 v19, v200, v19, vcc
	v_cmp_lt_u32_e32 vcc, s82, v37
	v_add_u32_e32 v37, 0xffffeffe, v36
	s_nop 0
	v_cndmask_b32_e32 v3, v200, v3, vcc
	v_cmp_lt_u32_e32 vcc, s82, v37
	v_add_u32_e32 v37, 0xffffefde, v36
	s_nop 0
	v_cndmask_b32_e32 v20, v200, v20, vcc
	v_cmp_lt_u32_e32 vcc, s82, v37
	v_add_u32_e32 v37, 0xffffeffd, v36
	s_nop 0
	v_cndmask_b32_e32 v4, v200, v4, vcc
	v_cmp_lt_u32_e32 vcc, s82, v37
	v_add_u32_e32 v37, 0xffffefdd, v36
	s_nop 0
	v_cndmask_b32_e32 v21, v200, v21, vcc
	v_cmp_lt_u32_e32 vcc, s82, v37
	v_add_u32_e32 v37, 0xffffeff8, v36
	s_nop 0
	v_cndmask_b32_e32 v5, v200, v5, vcc
	v_cmp_lt_u32_e32 vcc, s82, v37
	v_add_u32_e32 v37, 0xffffefd8, v36
	s_nop 0
	v_cndmask_b32_e32 v22, v200, v22, vcc
	v_cmp_lt_u32_e32 vcc, s82, v37
	v_add_u32_e32 v37, 0xffffeff7, v36
	s_nop 0
	v_cndmask_b32_e32 v6, v200, v6, vcc
	v_cmp_lt_u32_e32 vcc, s82, v37
	v_add_u32_e32 v37, 0xffffefd7, v36
	s_nop 0
	v_cndmask_b32_e32 v23, v200, v23, vcc
	v_cmp_lt_u32_e32 vcc, s82, v37
	v_add_u32_e32 v37, 0xffffeff6, v36
	s_nop 0
	v_cndmask_b32_e32 v7, v200, v7, vcc
	v_cmp_lt_u32_e32 vcc, s82, v37
	v_add_u32_e32 v37, 0xffffefd6, v36
	s_nop 0
	v_cndmask_b32_e32 v24, v200, v24, vcc
	v_cmp_lt_u32_e32 vcc, s82, v37
	v_add_u32_e32 v37, 0xffffeff5, v36
	s_nop 0
	v_cndmask_b32_e32 v8, v200, v8, vcc
	v_cmp_lt_u32_e32 vcc, s82, v37
	v_add_u32_e32 v37, 0xffffefd5, v36
	s_nop 0
	v_cndmask_b32_e32 v25, v200, v25, vcc
	v_cmp_lt_u32_e32 vcc, s82, v37
	v_add_u32_e32 v37, 0xffffeff0, v36
	s_nop 0
	v_cndmask_b32_e32 v9, v200, v9, vcc
	v_cmp_lt_u32_e32 vcc, s82, v37
	v_add_u32_e32 v37, 0xffffefd0, v36
	s_nop 0
	v_cndmask_b32_e32 v26, v200, v26, vcc
	v_cmp_lt_u32_e32 vcc, s82, v37
	v_add_u32_e32 v37, 0xffffefef, v36
	s_nop 0
	v_cndmask_b32_e32 v10, v200, v10, vcc
	v_cmp_lt_u32_e32 vcc, s82, v37
	v_add_u32_e32 v37, 0xffffefcf, v36
	s_nop 0
	v_cndmask_b32_e32 v27, v200, v27, vcc
	v_cmp_lt_u32_e32 vcc, s82, v37
	v_add_u32_e32 v37, 0xffffefee, v36
	s_nop 0
	v_cndmask_b32_e32 v11, v200, v11, vcc
	v_cmp_lt_u32_e32 vcc, s82, v37
	v_add_u32_e32 v37, 0xffffefce, v36
	s_nop 0
	v_cndmask_b32_e32 v28, v200, v28, vcc
	v_cmp_lt_u32_e32 vcc, s82, v37
	v_add_u32_e32 v37, 0xffffefed, v36
	s_nop 0
	v_cndmask_b32_e32 v12, v200, v12, vcc
	v_cmp_lt_u32_e32 vcc, s82, v37
	v_add_u32_e32 v37, 0xffffefcd, v36
	s_nop 0
	v_cndmask_b32_e32 v29, v200, v29, vcc
	v_cmp_lt_u32_e32 vcc, s82, v37
	v_add_u32_e32 v37, 0xffffefe8, v36
	s_nop 0
	v_cndmask_b32_e32 v13, v200, v13, vcc
	v_cmp_lt_u32_e32 vcc, s82, v37
	v_add_u32_e32 v37, 0xffffefc8, v36
	s_nop 0
	v_cndmask_b32_e32 v30, v200, v30, vcc
	v_cmp_lt_u32_e32 vcc, s82, v37
	v_add_u32_e32 v37, 0xffffefe7, v36
	s_nop 0
	v_cndmask_b32_e32 v14, v200, v14, vcc
	v_cmp_lt_u32_e32 vcc, s82, v37
	v_add_u32_e32 v37, 0xffffefc7, v36
	s_nop 0
	v_cndmask_b32_e32 v31, v200, v31, vcc
	v_cmp_lt_u32_e32 vcc, s82, v37
	v_add_u32_e32 v37, 0xffffefe6, v36
	s_nop 0
	v_cndmask_b32_e32 v15, v200, v15, vcc
	v_cmp_lt_u32_e32 vcc, s82, v37
	v_add_u32_e32 v37, 0xffffefc6, v36
	s_nop 0
	v_cndmask_b32_e32 v32, v200, v32, vcc
	v_cmp_lt_u32_e32 vcc, s82, v37
	v_add_u32_e32 v37, 0xffffefe5, v36
	v_add_u32_e32 v36, 0xffffefc5, v36
	v_cndmask_b32_e32 v16, v200, v16, vcc
	v_cmp_lt_u32_e32 vcc, s82, v37
	s_nop 1
	v_cndmask_b32_e32 v33, v200, v33, vcc
	v_cmp_lt_u32_e32 vcc, s82, v36
	s_nop 1
	v_cndmask_b32_e32 v17, v200, v17, vcc

; __device__ __forceinline__ void finishSM(f32x16& p0, f32x16& p1, float alpha, float& l_reg, bf16x8& pa0, bf16x8& pa1, bf16x8& pa2, bf16x8& pa3) {
;     for (int r = 0; r < 16; ++r) p1[r] = __builtin_amdgcn_exp2f(p1[r]);
;     float ps = 0; for (int r = 0; r < 16; ++r) ps += p0[r]; for (int r = 0; r < 16; ++r) ps += p1[r];
;     { auto rr = __builtin_amdgcn_permlane32_swap(__float_as_uint(ps), __float_as_uint(ps), false, false);
;       ps = __uint_as_float(rr[0]) + __uint_as_float(rr[1]); }
;     l_reg = l_reg * alpha + ps;
;     ...
;     PK4(p0, 0, pa0); PK4(p0, 8, pa1); PK4(p1, 0, pa2); PK4(p1, 8, pa3);
;     ...
; }
; template <int KB, bool SK>
; __device__ __forceinline__ void qkt(f32x16& p0, f32x16& p1, const char* K_lds, const float* B_lds, int r32, int hi, const bf16x8* qr, bool act) {
;     if (SK && !act) { const float NEG = -__builtin_inff();
; #pragma unroll
;         for (int r = 0; r < 16; ++r) { p0[r] = NEG; p1[r] = NEG; } return; }
;     ...
;     p0 = f32x16{}; p1 = f32x16{};
;     ...
;     p0 = *(const f32x16*)(B_lds + KB * 64 + hi * 32); p1 = *(const f32x16*)(B_lds + KB * 64 + hi * 32 + 16);
;     ...
;     const char* kb[4];
; #pragma unroll
;     for (int dd = 0; dd < 4; ++dd) kb[dd] = K_lds + KB * SHM_K + KSWZ(r32, (dd * 16 + hi * 8) * 2);
; #pragma unroll
;     for (int d0 = 0; d0 < 8; ++d0) { const char* a = kb[d0 & 3] + (d0 >> 2) * 128;
;         bf16x8 b0 = *reinterpret_cast<const bf16x8*>(a);
;         bf16x8 b1 = *reinterpret_cast<const bf16x8*>(a + 32 * 256);
;         p0 = __builtin_amdgcn_mfma_f32_32x32x16_bf16(b0, qr[d0], p0, 0, 0, 0);
;         p1 = __builtin_amdgcn_mfma_f32_32x32x16_bf16(b1, qr[d0], p1, 0, 0, 0); }
; }
.LBB0_1247:
	v_add_u32_e32 v0, 0x10900, v236
	ds_read_b128 v[100:103], v0
	ds_read_b128 v[104:107], v0 offset:16
	ds_read_b128 v[108:111], v0 offset:32
	s_waitcnt vmcnt(2)
	ds_read_b128 v[112:115], v0 offset:48
	ds_read_b128 v[96:99], v0 offset:112
	ds_read_b128 v[92:95], v0 offset:96
	ds_read_b128 v[88:91], v0 offset:80
	ds_read_b128 v[84:87], v0 offset:64
	ds_read_b128 v[6:9], v235 offset:49152
	ds_read_b128 v[214:217], v235 offset:57344
	ds_read_b128 v[2:5], v234 offset:49152
	v_add_f32_e32 v80, 0, v191
	v_add_f32_e32 v80, v193, v80
	v_add_f32_e32 v80, v189, v80
	s_waitcnt lgkmcnt(2)
	v_mfma_f32_32x32x16_bf16 v[100:115], v[6:9], v[172:175], v[100:115]
	ds_read_b128 v[6:9], v234 offset:57344
	v_add_f32_e32 v80, v192, v80
	v_add_f32_e32 v80, v188, v80
	v_add_f32_e32 v80, v190, v80
	v_add_f32_e32 v80, v186, v80
	v_add_f32_e32 v80, v187, v80
	v_add_f32_e32 v80, v182, v80
	v_add_f32_e32 v80, v185, v80
	s_waitcnt lgkmcnt(2)
	v_mfma_f32_32x32x16_bf16 v[84:99], v[214:217], v[172:175], v[84:99]
	ds_read_b128 v[214:217], v233 offset:49152
	v_add_f32_e32 v80, v179, v80
	v_add_f32_e32 v80, v183, v80
	v_exp_f32_e32 v0, v142
	v_add_f32_e32 v80, v177, v80
	v_add_f32_e32 v80, v184, v80
	v_add_f32_e32 v80, v178, v80
	s_waitcnt lgkmcnt(2)
	v_mfma_f32_32x32x16_bf16 v[100:115], v[2:5], v[168:171], v[100:115]
	ds_read_b128 v[2:5], v233 offset:57344
	v_add_f32_e32 v80, v181, v80
	v_add_f32_e32 v80, v0, v80
	v_exp_f32_e32 v10, v135
	v_exp_f32_e32 v11, v132
	v_exp_f32_e32 v12, v133
	v_exp_f32_e32 v13, v130
	v_exp_f32_e32 v15, v131
	s_waitcnt lgkmcnt(2)
	v_mfma_f32_32x32x16_bf16 v[84:99], v[6:9], v[168:171], v[84:99]
	ds_read_b128 v[6:9], v232 offset:49152
	v_exp_f32_e32 v127, v128
	v_exp_f32_e32 v128, v129
	s_sub_i32 s4, s68, 63
	s_waitcnt lgkmcnt(2)
	v_mfma_f32_32x32x16_bf16 v[100:115], v[214:217], v[164:167], v[100:115]
	ds_read_b128 v[214:217], v232 offset:57344
	s_waitcnt lgkmcnt(2)
	v_mfma_f32_32x32x16_bf16 v[84:99], v[2:5], v[164:167], v[84:99]
	ds_read_b128 v[2:5], v235 offset:49280
	s_waitcnt lgkmcnt(2)
	v_mfma_f32_32x32x16_bf16 v[100:115], v[6:9], v[160:163], v[100:115]
	ds_read_b128 v[6:9], v235 offset:57472
	s_waitcnt lgkmcnt(2)
	v_mfma_f32_32x32x16_bf16 v[84:99], v[214:217], v[160:163], v[84:99]
	ds_read_b128 v[214:217], v234 offset:49280
	s_waitcnt lgkmcnt(2)
	v_mfma_f32_32x32x16_bf16 v[100:115], v[2:5], v[156:159], v[100:115]
	ds_read_b128 v[2:5], v234 offset:57472
	s_waitcnt lgkmcnt(2)
	v_mfma_f32_32x32x16_bf16 v[84:99], v[6:9], v[156:159], v[84:99]
	ds_read_b128 v[6:9], v233 offset:49280
	s_waitcnt lgkmcnt(2)
	v_mfma_f32_32x32x16_bf16 v[100:115], v[214:217], v[152:155], v[100:115]
	ds_read_b128 v[214:217], v233 offset:57472
	s_waitcnt lgkmcnt(2)
	v_mfma_f32_32x32x16_bf16 v[84:99], v[2:5], v[152:155], v[84:99]
	ds_read_b128 v[2:5], v232 offset:49280
	s_waitcnt lgkmcnt(2)
	v_mfma_f32_32x32x16_bf16 v[100:115], v[6:9], v[148:151], v[100:115]
	ds_read_b128 v[6:9], v232 offset:57472
	s_waitcnt lgkmcnt(2)
	v_mfma_f32_32x32x16_bf16 v[84:99], v[214:217], v[148:151], v[84:99]
	s_waitcnt lgkmcnt(1)
	v_mfma_f32_32x32x16_bf16 v[100:115], v[2:5], v[144:147], v[100:115]
	v_exp_f32_e32 v2, v143
	v_exp_f32_e32 v3, v140
	v_exp_f32_e32 v4, v141
	v_exp_f32_e32 v5, v138
	v_add_f32_e32 v80, v2, v80
	v_add_f32_e32 v80, v3, v80
	v_add_f32_e32 v80, v4, v80
	s_waitcnt lgkmcnt(0)
	v_mfma_f32_32x32x16_bf16 v[84:99], v[6:9], v[144:147], v[84:99]
	v_exp_f32_e32 v6, v139
	v_exp_f32_e32 v7, v136
	v_exp_f32_e32 v8, v137
	v_exp_f32_e32 v9, v134
	v_add_f32_e32 v80, v5, v80
	v_add_f32_e32 v80, v6, v80
	v_add_f32_e32 v80, v7, v80
	v_add_f32_e32 v80, v8, v80
	v_add_f32_e32 v80, v9, v80
	v_add_f32_e32 v80, v10, v80
	v_add_f32_e32 v80, v11, v80
	v_add_f32_e32 v80, v12, v80
	v_add_f32_e32 v80, v13, v80
	v_add_f32_e32 v80, v15, v80
	v_add_f32_e32 v80, v127, v80
	v_add_f32_e32 v244, v128, v80
	v_mov_b32_e32 v245, v244
	s_nop 1
	v_permlane32_swap_b32_e32 v244, v245
	v_cvt_pk_bf16_f32 v80, v191, v193
	v_cvt_pk_bf16_f32 v81, v189, v192
	v_cvt_pk_bf16_f32 v82, v188, v190
	v_cvt_pk_bf16_f32 v83, v186, v187
	s_waitcnt vmcnt(1)
	v_cvt_pk_bf16_f32 v116, v182, v185
	v_cvt_pk_bf16_f32 v117, v179, v183
	v_cvt_pk_bf16_f32 v118, v177, v184
	v_cvt_pk_bf16_f32 v119, v178, v181
	s_waitcnt vmcnt(0)
	v_cvt_pk_bf16_f32 v120, v0, v2
	v_cvt_pk_bf16_f32 v121, v3, v4
	v_cvt_pk_bf16_f32 v122, v5, v6
	v_cvt_pk_bf16_f32 v123, v7, v8
	v_cvt_pk_bf16_f32 v124, v9, v10
	v_cvt_pk_bf16_f32 v125, v11, v12
	v_cvt_pk_bf16_f32 v126, v13, v15
	v_cvt_pk_bf16_f32 v127, v127, v128
	v_permlane32_swap_b32_e32 v80, v82
	v_permlane32_swap_b32_e32 v81, v83
	v_permlane32_swap_b32_e32 v116, v118
	v_permlane32_swap_b32_e32 v117, v119
	v_permlane32_swap_b32_e32 v120, v122
	v_permlane32_swap_b32_e32 v121, v123
	v_permlane32_swap_b32_e32 v124, v126
	v_permlane32_swap_b32_e32 v125, v127
	v_add_u32_e32 v0, v230, v219
	v_add_u32_e32 v248, s68, v0
	v_add_u32_e32 v0, 1, v248
	v_lshl_add_u64 v[2:3], v[0:1], 2, s[66:67]
	v_mov_b32_e32 v15, v1
	v_add_u32_e32 v0, 0x10000, v14
	v_lshlrev_b64 v[10:11], 1, v[14:15]
	v_lshlrev_b64 v[12:13], 1, v[0:1]
	global_load_dword v246, v[2:3], off
	v_lshl_add_u64 v[2:3], s[64:65], 0, v[10:11]
	v_lshl_add_u64 v[6:7], s[64:65], 0, v[12:13]
	v_lshl_add_u64 v[10:11], s[62:63], 0, v[10:11]
	global_load_dwordx4 v[2:5], v[2:3], off
	s_nop 0
	global_load_dwordx4 v[6:9], v[6:7], off
	v_lshl_add_u64 v[128:129], s[62:63], 0, v[12:13]
	global_load_dwordx4 v[10:13], v[10:11], off
	s_nop 0
	global_load_dwordx4 v[176:179], v[128:129], off
	ds_read_b64_tr_b16 v[128:129], v227 offset:0
	ds_read_b64_tr_b16 v[130:131], v227 offset:0x800
	ds_read_b64_tr_b16 v[132:133], v227 offset:0x1000
	ds_read_b64_tr_b16 v[134:135], v227 offset:0x1800
	ds_read_b64_tr_b16 v[136:137], v227 offset:0x2000
	ds_read_b64_tr_b16 v[138:139], v227 offset:0x2800
	ds_read_b64_tr_b16 v[140:141], v227 offset:0x3000
	ds_read_b64_tr_b16 v[142:143], v227 offset:0x3800
	s_waitcnt lgkmcnt(0)
; __device__ __forceinline__ void mask_tile(f32x16& p0, f32x16& p1, int dq, unsigned W) {
;     const float NEG = -__builtin_inff();
; #pragma unroll
;     for (int r = 0; r < 16; ++r) {
;         const int c = (r & 3) + 8 * (r >> 2);
;         if ((unsigned)(dq - c) >= W) p0[r] = NEG;
;         if ((unsigned)(dq - c - 32) >= W) p1[r] = NEG;
;     }
; }
; template <int VB, bool SK>
; __device__ __forceinline__ void pv_tile(f32x16* o, int vb0, bf16x8 pa0, bf16x8 pa1, bf16x8 pa2, bf16x8 pa3, bool act) {
;     if (SK && !act) return;
;     ...
;     PV_D0(0); PV_D0(1); PV_D0(2); PV_D0(3);
	s_nop 0
	v_mfma_f32_32x32x16_bf16 v[64:79], v[80:83], v[128:131], v[64:79]
	ds_read_b64_tr_b16 v[128:129], v227 offset:0x200
	ds_read_b64_tr_b16 v[130:131], v227 offset:0xa00
	v_mfma_f32_32x32x16_bf16 v[64:79], v[116:119], v[132:135], v[64:79]
	ds_read_b64_tr_b16 v[132:133], v227 offset:0x1200
	ds_read_b64_tr_b16 v[134:135], v227 offset:0x1a00
	v_mfma_f32_32x32x16_bf16 v[64:79], v[120:123], v[136:139], v[64:79]
	ds_read_b64_tr_b16 v[136:137], v227 offset:0x2200
	ds_read_b64_tr_b16 v[138:139], v227 offset:0x2a00
	v_mfma_f32_32x32x16_bf16 v[64:79], v[124:127], v[140:143], v[64:79]
	ds_read_b64_tr_b16 v[140:141], v227 offset:0x3200
	ds_read_b64_tr_b16 v[142:143], v227 offset:0x3a00
	s_waitcnt lgkmcnt(0)
	v_mfma_f32_32x32x16_bf16 v[48:63], v[80:83], v[128:131], v[48:63]
	ds_read_b64_tr_b16 v[128:129], v227 offset:0x400
	ds_read_b64_tr_b16 v[130:131], v227 offset:0xc00
	v_mfma_f32_32x32x16_bf16 v[48:63], v[116:119], v[132:135], v[48:63]
	ds_read_b64_tr_b16 v[132:133], v227 offset:0x1400
	ds_read_b64_tr_b16 v[134:135], v227 offset:0x1c00
	v_mfma_f32_32x32x16_bf16 v[48:63], v[120:123], v[136:139], v[48:63]
	ds_read_b64_tr_b16 v[136:137], v227 offset:0x2400
	ds_read_b64_tr_b16 v[138:139], v227 offset:0x2c00
	v_mfma_f32_32x32x16_bf16 v[48:63], v[124:127], v[140:143], v[48:63]
	ds_read_b64_tr_b16 v[140:141], v227 offset:0x3400
	ds_read_b64_tr_b16 v[142:143], v227 offset:0x3c00
	s_waitcnt lgkmcnt(0)
	v_mfma_f32_32x32x16_bf16 v[32:47], v[80:83], v[128:131], v[32:47]
	ds_read_b64_tr_b16 v[128:129], v227 offset:0x600
	ds_read_b64_tr_b16 v[130:131], v227 offset:0xe00
	v_mfma_f32_32x32x16_bf16 v[32:47], v[116:119], v[132:135], v[32:47]
	ds_read_b64_tr_b16 v[132:133], v227 offset:0x1600
	ds_read_b64_tr_b16 v[134:135], v227 offset:0x1e00
	v_mfma_f32_32x32x16_bf16 v[32:47], v[120:123], v[136:139], v[32:47]
	ds_read_b64_tr_b16 v[136:137], v227 offset:0x2600
	ds_read_b64_tr_b16 v[138:139], v227 offset:0x2e00
	v_mfma_f32_32x32x16_bf16 v[32:47], v[124:127], v[140:143], v[32:47]
	ds_read_b64_tr_b16 v[140:141], v227 offset:0x3600
	ds_read_b64_tr_b16 v[142:143], v227 offset:0x3e00
	s_waitcnt lgkmcnt(0)
	v_mfma_f32_32x32x16_bf16 v[16:31], v[80:83], v[128:131], v[16:31]
	s_cmp_le_i32 s68, s57
	s_cselect_b64 s[28:29], -1, 0
	s_cmp_gt_i32 s4, s58
	s_cselect_b64 s[4:5], -1, 0
	s_and_b64 s[4:5], s[28:29], s[4:5]
	s_and_b64 vcc, exec, s[4:5]
	v_mfma_f32_32x32x16_bf16 v[16:31], v[116:119], v[132:135], v[16:31]
	v_mfma_f32_32x32x16_bf16 v[16:31], v[120:123], v[136:139], v[16:31]
	v_mfma_f32_32x32x16_bf16 v[16:31], v[124:127], v[140:143], v[16:31]
	s_cbranch_vccnz .LBB0_1249
	v_add_u32_e32 v0, 0x107b, v243
	v_cmp_gt_u32_e32 vcc, s81, v0
	v_add_u32_e32 v0, 0x5b, v243
	s_nop 0
	v_cndmask_b32_e32 v100, v200, v100, vcc
	v_cmp_lt_u32_e32 vcc, s82, v0
	v_add_u32_e32 v0, 0x7a, v243
	s_nop 0
	v_cndmask_b32_e32 v84, v200, v84, vcc
	v_cmp_lt_u32_e32 vcc, s82, v0
	v_add_u32_e32 v0, 0x5a, v243
	s_nop 0
	v_cndmask_b32_e32 v101, v200, v101, vcc
	v_cmp_lt_u32_e32 vcc, s82, v0
	v_add_u32_e32 v0, 0x79, v243
	s_nop 0
	v_cndmask_b32_e32 v85, v200, v85, vcc
	v_cmp_lt_u32_e32 vcc, s82, v0
	v_add_u32_e32 v0, 0x59, v243
	s_nop 0
	v_cndmask_b32_e32 v102, v200, v102, vcc
	v_cmp_lt_u32_e32 vcc, s82, v0
	v_add_u32_e32 v0, 0x78, v243
	s_nop 0
	v_cndmask_b32_e32 v86, v200, v86, vcc
	v_cmp_lt_u32_e32 vcc, s82, v0
	v_add_u32_e32 v0, 0x58, v243
	s_nop 0
	v_cndmask_b32_e32 v103, v200, v103, vcc
	v_cmp_lt_u32_e32 vcc, s82, v0
	v_add_u32_e32 v0, 0x73, v243
	s_nop 0
	v_cndmask_b32_e32 v87, v200, v87, vcc
	v_cmp_lt_u32_e32 vcc, s82, v0
	v_add_u32_e32 v0, 0x53, v243
	s_nop 0
	v_cndmask_b32_e32 v104, v200, v104, vcc
	v_cmp_lt_u32_e32 vcc, s82, v0
	v_add_u32_e32 v0, 0x72, v243
	s_nop 0
	v_cndmask_b32_e32 v88, v200, v88, vcc
	v_cmp_lt_u32_e32 vcc, s82, v0
	v_add_u32_e32 v0, 0x52, v243
	s_nop 0
	v_cndmask_b32_e32 v105, v200, v105, vcc
	v_cmp_lt_u32_e32 vcc, s82, v0
	v_add_u32_e32 v0, 0x71, v243
	s_nop 0
	v_cndmask_b32_e32 v89, v200, v89, vcc
	v_cmp_lt_u32_e32 vcc, s82, v0
	v_add_u32_e32 v0, 0x51, v243
	s_nop 0
	v_cndmask_b32_e32 v106, v200, v106, vcc
	v_cmp_lt_u32_e32 vcc, s82, v0
	v_add_u32_e32 v0, 0x70, v243
	s_nop 0
	v_cndmask_b32_e32 v90, v200, v90, vcc
	v_cmp_lt_u32_e32 vcc, s82, v0
	v_add_u32_e32 v0, 0x50, v243
	s_nop 0
	v_cndmask_b32_e32 v107, v200, v107, vcc
	v_cmp_lt_u32_e32 vcc, s82, v0
	v_add_u32_e32 v0, 0x6b, v243
	s_nop 0
	v_cndmask_b32_e32 v91, v200, v91, vcc
	v_cmp_lt_u32_e32 vcc, s82, v0
	v_add_u32_e32 v0, 0x4b, v243
	s_nop 0
	v_cndmask_b32_e32 v108, v200, v108, vcc
	v_cmp_lt_u32_e32 vcc, s82, v0
	v_add_u32_e32 v0, 0x6a, v243
	s_nop 0
	v_cndmask_b32_e32 v92, v200, v92, vcc
	v_cmp_lt_u32_e32 vcc, s82, v0
	v_add_u32_e32 v0, 0x4a, v243
	s_nop 0
	v_cndmask_b32_e32 v109, v200, v109, vcc
	v_cmp_lt_u32_e32 vcc, s82, v0
	v_add_u32_e32 v0, 0x69, v243
	s_nop 0
	v_cndmask_b32_e32 v93, v200, v93, vcc
	v_cmp_lt_u32_e32 vcc, s82, v0
	v_add_u32_e32 v0, 0x49, v243
	s_nop 0
	v_cndmask_b32_e32 v110, v200, v110, vcc
	v_cmp_lt_u32_e32 vcc, s82, v0
	v_add_u32_e32 v0, 0x68, v243
	s_nop 0
	v_cndmask_b32_e32 v94, v200, v94, vcc
	v_cmp_lt_u32_e32 vcc, s82, v0
	v_add_u32_e32 v0, 0x48, v243
	s_nop 0
	v_cndmask_b32_e32 v111, v200, v111, vcc
	v_cmp_lt_u32_e32 vcc, s82, v0
	v_add_u32_e32 v0, 0x63, v243
	s_nop 0
	v_cndmask_b32_e32 v95, v200, v95, vcc
	v_cmp_lt_u32_e32 vcc, s82, v0
	v_add_u32_e32 v0, 0x43, v243
	s_nop 0
	v_cndmask_b32_e32 v112, v200, v112, vcc
	v_cmp_lt_u32_e32 vcc, s82, v0
	v_add_u32_e32 v0, 0x62, v243
	s_nop 0
	v_cndmask_b32_e32 v96, v200, v96, vcc
	v_cmp_lt_u32_e32 vcc, s82, v0
	v_add_u32_e32 v0, 0x42, v243
	s_nop 0
	v_cndmask_b32_e32 v113, v200, v113, vcc
	v_cmp_lt_u32_e32 vcc, s82, v0
	v_add_u32_e32 v0, 0x61, v243
	s_nop 0
	v_cndmask_b32_e32 v97, v200, v97, vcc
	v_cmp_lt_u32_e32 vcc, s82, v0
	v_add_u32_e32 v0, 0x41, v243
	s_nop 0
	v_cndmask_b32_e32 v114, v200, v114, vcc
	v_cmp_lt_u32_e32 vcc, s82, v0
	v_add_u32_e32 v0, 0x60, v243
	s_nop 0
	v_cndmask_b32_e32 v98, v200, v98, vcc
	v_cmp_lt_u32_e32 vcc, s82, v0
	v_add_u32_e32 v0, 64, v243
	s_nop 0
	v_cndmask_b32_e32 v115, v200, v115, vcc
	v_cmp_lt_u32_e32 vcc, s82, v0
	s_nop 1
	v_cndmask_b32_e32 v99, v200, v99, vcc

; __device__ __forceinline__ void partialSM(f32x16& p0, f32x16& p1, float& m_reg, float& mn, float& alpha) {
;     float pmax = p0[0]; for (int r = 1; r < 16; ++r) pmax = fmaxf(pmax, p0[r]); for (int r = 0; r < 16; ++r) pmax = fmaxf(pmax, p1[r]);
;     { auto rr = __builtin_amdgcn_permlane32_swap(__float_as_uint(pmax), __float_as_uint(pmax), false, false);
;       pmax = fmaxf(__uint_as_float(rr[0]), __uint_as_float(rr[1])); }
;     constexpr float C2 = 1.4426950408889634f * SCALE;
;     if (__builtin_expect(__all((pmax - m_reg) * SCALE <= THR), 1)) { mn = m_reg; alpha = 1.f; }
;     else { mn = fmaxf(m_reg, pmax); alpha = __builtin_amdgcn_exp2f((m_reg - mn) * C2); m_reg = mn; }
;     const float mnL = -mn * C2;
;     for (int r = 0; r < 16; ++r) p0[r] = fmaf(p0[r], C2, mnL); for (int r = 0; r < 16; ++r) p1[r] = fmaf(p1[r], C2, mnL);
;     for (int r = 0; r < 16; ++r) p0[r] = __builtin_amdgcn_exp2f(p0[r]);
; }
; __device__ __forceinline__ void finishSM(f32x16& p0, f32x16& p1, float alpha, float& l_reg, bf16x8& pa0, bf16x8& pa1, bf16x8& pa2, bf16x8& pa3) {
;     for (int r = 0; r < 16; ++r) p1[r] = __builtin_amdgcn_exp2f(p1[r]);
;     float ps = 0; for (int r = 0; r < 16; ++r) ps += p0[r]; for (int r = 0; r < 16; ++r) ps += p1[r];
;     { auto rr = __builtin_amdgcn_permlane32_swap(__float_as_uint(ps), __float_as_uint(ps), false, false);
;       ps = __uint_as_float(rr[0]) + __uint_as_float(rr[1]); }
;     l_reg = l_reg * alpha + ps;
;     ...
;     PK4(p0, 0, pa0); PK4(p0, 8, pa1); PK4(p1, 0, pa2); PK4(p1, 8, pa3);
;     ...
; }
; template <int KB, bool SK>
; __device__ __forceinline__ void qkt(f32x16& p0, f32x16& p1, const char* K_lds, const float* B_lds, int r32, int hi, const bf16x8* qr, bool act) {
;     if (SK && !act) { const float NEG = -__builtin_inff();
; #pragma unroll
;         for (int r = 0; r < 16; ++r) { p0[r] = NEG; p1[r] = NEG; } return; }
;     ...
;     p0 = f32x16{}; p1 = f32x16{};
;     ...
;     p0 = *(const f32x16*)(B_lds + KB * 64 + hi * 32); p1 = *(const f32x16*)(B_lds + KB * 64 + hi * 32 + 16);
;     ...
;     const char* kb[4];
; #pragma unroll
;     for (int dd = 0; dd < 4; ++dd) kb[dd] = K_lds + KB * SHM_K + KSWZ(r32, (dd * 16 + hi * 8) * 2);
; #pragma unroll
;     for (int d0 = 0; d0 < 8; ++d0) { const char* a = kb[d0 & 3] + (d0 >> 2) * 128;
;         bf16x8 b0 = *reinterpret_cast<const bf16x8*>(a);
;         bf16x8 b1 = *reinterpret_cast<const bf16x8*>(a + 32 * 256);
.LBB0_1253:
	v_cndmask_b32_e64 v247, v0, v180, s[4:5]
	v_mul_f32_e32 v0, 0xbe0293ee, v247
	v_fmamk_f32 v80, v100, 0x3e0293ee, v0
	v_fmamk_f32 v81, v101, 0x3e0293ee, v0
	v_fmamk_f32 v82, v102, 0x3e0293ee, v0
	v_fmamk_f32 v83, v103, 0x3e0293ee, v0
	v_fmamk_f32 v116, v104, 0x3e0293ee, v0
	v_fmamk_f32 v117, v105, 0x3e0293ee, v0
	v_fmamk_f32 v118, v106, 0x3e0293ee, v0
	v_fmamk_f32 v119, v107, 0x3e0293ee, v0
	v_fmamk_f32 v120, v108, 0x3e0293ee, v0
	v_fmamk_f32 v121, v109, 0x3e0293ee, v0
	v_fmamk_f32 v122, v110, 0x3e0293ee, v0
	v_fmamk_f32 v123, v111, 0x3e0293ee, v0
	v_fmamk_f32 v112, v112, 0x3e0293ee, v0
	v_fmamk_f32 v113, v113, 0x3e0293ee, v0
	v_fmamk_f32 v114, v114, 0x3e0293ee, v0
	v_fmamk_f32 v115, v115, 0x3e0293ee, v0
	v_fmamk_f32 v100, v84, 0x3e0293ee, v0
	v_fmamk_f32 v109, v85, 0x3e0293ee, v0
	v_fmamk_f32 v110, v86, 0x3e0293ee, v0
	v_fmamk_f32 v111, v87, 0x3e0293ee, v0
	v_fmamk_f32 v180, v88, 0x3e0293ee, v0
	v_fmamk_f32 v101, v89, 0x3e0293ee, v0
	v_fmamk_f32 v102, v90, 0x3e0293ee, v0
	v_fmamk_f32 v103, v91, 0x3e0293ee, v0
	v_fmamk_f32 v104, v92, 0x3e0293ee, v0
	v_fmamk_f32 v105, v93, 0x3e0293ee, v0
	v_fmamk_f32 v106, v94, 0x3e0293ee, v0
	v_fmamk_f32 v107, v95, 0x3e0293ee, v0
	v_exp_f32_e32 v80, v80
	v_exp_f32_e32 v81, v81
	v_exp_f32_e32 v82, v82
	v_exp_f32_e32 v83, v83
	v_exp_f32_e32 v84, v116
	v_exp_f32_e32 v85, v117
	v_exp_f32_e32 v86, v118
	v_exp_f32_e32 v87, v119
	v_exp_f32_e32 v88, v120
	v_exp_f32_e32 v89, v121
	v_exp_f32_e32 v90, v122
	v_exp_f32_e32 v91, v123
	v_exp_f32_e32 v92, v112
	v_exp_f32_e32 v93, v113
	v_exp_f32_e32 v94, v114
	v_exp_f32_e32 v95, v115
	v_fmamk_f32 v108, v96, 0x3e0293ee, v0
	v_fmamk_f32 v181, v97, 0x3e0293ee, v0
	v_fmamk_f32 v182, v98, 0x3e0293ee, v0
	v_fmac_f32_e32 v0, 0x3e0293ee, v99
	s_waitcnt lgkmcnt(0)
	s_barrier
	ds_read_b128 v[128:131], v239
	ds_read_b128 v[132:135], v239 offset:16
	ds_read_b128 v[136:139], v239 offset:32
	ds_read_b128 v[140:143], v239 offset:48
	ds_read_b128 v[124:127], v239 offset:112
	ds_read_b128 v[120:123], v239 offset:96
	ds_read_b128 v[116:119], v239 offset:80
	ds_read_b128 v[112:115], v239 offset:64
	ds_read_b128 v[184:187], v235 offset:32768
	ds_read_b128 v[214:217], v235 offset:40960
	ds_read_b128 v[96:99], v234 offset:32768
	v_exp_f32_e32 v101, v101
	v_exp_f32_e32 v102, v102
	v_exp_f32_e32 v103, v103
	s_waitcnt lgkmcnt(2)
	v_mfma_f32_32x32x16_bf16 v[128:143], v[184:187], v[172:175], v[128:143]
	ds_read_b128 v[184:187], v234 offset:40960
	v_exp_f32_e32 v104, v104
	v_exp_f32_e32 v105, v105
	v_exp_f32_e32 v106, v106
	v_exp_f32_e32 v107, v107
	v_exp_f32_e32 v108, v108
	s_waitcnt lgkmcnt(2)
	v_mfma_f32_32x32x16_bf16 v[112:127], v[214:217], v[172:175], v[112:127]
	ds_read_b128 v[214:217], v233 offset:32768
	s_waitcnt lgkmcnt(2)
	v_mfma_f32_32x32x16_bf16 v[128:143], v[96:99], v[168:171], v[128:143]
	ds_read_b128 v[96:99], v233 offset:40960
	s_waitcnt lgkmcnt(2)
	v_mfma_f32_32x32x16_bf16 v[112:127], v[184:187], v[168:171], v[112:127]
	ds_read_b128 v[184:187], v232 offset:32768
	s_waitcnt lgkmcnt(2)
	v_mfma_f32_32x32x16_bf16 v[128:143], v[214:217], v[164:167], v[128:143]
	ds_read_b128 v[214:217], v232 offset:40960
	s_waitcnt lgkmcnt(2)
	v_mfma_f32_32x32x16_bf16 v[112:127], v[96:99], v[164:167], v[112:127]
	ds_read_b128 v[96:99], v235 offset:32896
	s_waitcnt lgkmcnt(2)
	v_mfma_f32_32x32x16_bf16 v[128:143], v[184:187], v[160:163], v[128:143]
	ds_read_b128 v[184:187], v235 offset:41088
	s_waitcnt lgkmcnt(2)
	v_mfma_f32_32x32x16_bf16 v[112:127], v[214:217], v[160:163], v[112:127]
	ds_read_b128 v[214:217], v234 offset:32896
	s_waitcnt lgkmcnt(2)
	v_mfma_f32_32x32x16_bf16 v[128:143], v[96:99], v[156:159], v[128:143]
	ds_read_b128 v[96:99], v234 offset:41088
	s_waitcnt lgkmcnt(2)
	v_mfma_f32_32x32x16_bf16 v[112:127], v[184:187], v[156:159], v[112:127]
	ds_read_b128 v[184:187], v233 offset:32896
	s_waitcnt lgkmcnt(2)
	v_mfma_f32_32x32x16_bf16 v[128:143], v[214:217], v[152:155], v[128:143]
	ds_read_b128 v[214:217], v233 offset:41088
	s_waitcnt lgkmcnt(2)
	v_mfma_f32_32x32x16_bf16 v[112:127], v[96:99], v[152:155], v[112:127]
	ds_read_b128 v[96:99], v232 offset:32896
	s_waitcnt lgkmcnt(2)
	v_mfma_f32_32x32x16_bf16 v[128:143], v[184:187], v[148:151], v[128:143]
	ds_read_b128 v[184:187], v232 offset:41088
	s_waitcnt lgkmcnt(2)
	v_mfma_f32_32x32x16_bf16 v[112:127], v[214:217], v[148:151], v[112:127]
	s_waitcnt lgkmcnt(1)
	v_mfma_f32_32x32x16_bf16 v[128:143], v[96:99], v[144:147], v[128:143]
	v_exp_f32_e32 v99, v111
	v_exp_f32_e32 v111, v0
	v_add_f32_e32 v0, 0, v80
	v_add_f32_e32 v0, v81, v0
	v_add_f32_e32 v0, v82, v0
	v_add_f32_e32 v0, v83, v0
	v_add_f32_e32 v0, v84, v0
	v_add_f32_e32 v0, v85, v0
	v_add_f32_e32 v0, v86, v0
	v_add_f32_e32 v0, v87, v0
	v_add_f32_e32 v0, v88, v0
	v_add_f32_e32 v0, v89, v0
	v_add_f32_e32 v0, v90, v0
	v_add_f32_e32 v0, v91, v0
	v_exp_f32_e32 v96, v100
	v_add_f32_e32 v0, v92, v0
	v_exp_f32_e32 v97, v109
	v_add_f32_e32 v0, v93, v0
	v_exp_f32_e32 v98, v110
	v_add_f32_e32 v0, v94, v0
	v_add_f32_e32 v0, v95, v0
	v_exp_f32_e32 v100, v180
	v_add_f32_e32 v0, v96, v0
	v_add_f32_e32 v0, v97, v0
	v_add_f32_e32 v0, v98, v0
	v_add_f32_e32 v0, v99, v0
	v_add_f32_e32 v0, v100, v0
	v_add_f32_e32 v0, v101, v0
	v_add_f32_e32 v0, v102, v0
	v_add_f32_e32 v0, v103, v0
	v_add_f32_e32 v0, v104, v0
	v_exp_f32_e32 v109, v181
	v_add_f32_e32 v0, v105, v0
	s_waitcnt lgkmcnt(0)
	v_mfma_f32_32x32x16_bf16 v[112:127], v[184:187], v[144:147], v[112:127]
	v_exp_f32_e32 v110, v182
	v_add_f32_e32 v0, v106, v0
	v_add_f32_e32 v0, v107, v0
	v_add_f32_e32 v0, v108, v0
	v_add_f32_e32 v0, v109, v0
	v_add_f32_e32 v0, v110, v0
	v_add_f32_e32 v249, v111, v0
	v_mov_b32_e32 v250, v249
	v_cvt_pk_bf16_f32 v180, v80, v81
	v_cvt_pk_bf16_f32 v181, v82, v83
	v_cvt_pk_bf16_f32 v182, v84, v85
	v_cvt_pk_bf16_f32 v183, v86, v87
	v_cvt_pk_bf16_f32 v184, v88, v89
	v_cvt_pk_bf16_f32 v185, v90, v91
	v_cvt_pk_bf16_f32 v186, v92, v93
	v_cvt_pk_bf16_f32 v187, v94, v95
	v_cvt_pk_bf16_f32 v188, v96, v97
	v_cvt_pk_bf16_f32 v189, v98, v99
	v_cvt_pk_bf16_f32 v190, v100, v101
	v_cvt_pk_bf16_f32 v191, v102, v103
	v_cvt_pk_bf16_f32 v192, v104, v105
	v_cvt_pk_bf16_f32 v193, v106, v107
	v_cvt_pk_bf16_f32 v194, v108, v109
	v_cvt_pk_bf16_f32 v195, v110, v111
	s_nop 1
	v_permlane32_swap_b32_e32 v249, v250
	v_permlane32_swap_b32_e32 v180, v182
	v_permlane32_swap_b32_e32 v181, v183
	v_permlane32_swap_b32_e32 v184, v186
	v_permlane32_swap_b32_e32 v185, v187
	v_permlane32_swap_b32_e32 v188, v190
	v_permlane32_swap_b32_e32 v189, v191
	v_permlane32_swap_b32_e32 v192, v194
	v_permlane32_swap_b32_e32 v193, v195
	s_add_i32 s4, s61, 1
	s_cmp_lt_i32 s4, s59
	s_cselect_b64 s[28:29], -1, 0
	s_cmp_ge_i32 s4, s59
	s_cbranch_scc1 .LBB0_1255
	v_add_u32_e32 v0, 0x41, v248
	v_lshl_add_u64 v[2:3], v[0:1], 2, s[66:67]
	v_add_u32_e32 v0, 0x20000, v14
	v_lshlrev_b64 v[10:11], 1, v[0:1]
	v_add_u32_e32 v0, 0x30000, v14
	v_lshlrev_b64 v[12:13], 1, v[0:1]
	global_load_dword v246, v[2:3], off
	v_lshl_add_u64 v[2:3], s[64:65], 0, v[10:11]
	v_lshl_add_u64 v[6:7], s[64:65], 0, v[12:13]
	v_lshl_add_u64 v[10:11], s[62:63], 0, v[10:11]
	v_lshl_add_u64 v[176:177], s[62:63], 0, v[12:13]
	global_load_dwordx4 v[2:5], v[2:3], off
	s_nop 0
	global_load_dwordx4 v[6:9], v[6:7], off
	s_nop 0
	global_load_dwordx4 v[10:13], v[10:11], off
	s_nop 0
	global_load_dwordx4 v[176:179], v[176:177], off
; __device__ __forceinline__ void mask_tile(f32x16& p0, f32x16& p1, int dq, unsigned W) {
;     const float NEG = -__builtin_inff();
; #pragma unroll
;     for (int r = 0; r < 16; ++r) {
;         const int c = (r & 3) + 8 * (r >> 2);
;         if ((unsigned)(dq - c) >= W) p0[r] = NEG;
;         if ((unsigned)(dq - c - 32) >= W) p1[r] = NEG;
;     }
; }
; template <int VB, bool SK>
; __device__ __forceinline__ void pv_tile(f32x16* o, int vb0, bf16x8 pa0, bf16x8 pa1, bf16x8 pa2, bf16x8 pa3, bool act) {
;     if (SK && !act) return;
;     ...
;     PV_D0(0); PV_D0(1); PV_D0(2); PV_D0(3);
.LBB0_1255:
	ds_read_b64_tr_b16 v[202:203], v227 offset:0x4000
	ds_read_b64_tr_b16 v[204:205], v227 offset:0x4800
	ds_read_b64_tr_b16 v[196:197], v227 offset:0x5000
	ds_read_b64_tr_b16 v[198:199], v227 offset:0x5800
	ds_read_b64_tr_b16 v[210:211], v227 offset:0x6000
	ds_read_b64_tr_b16 v[212:213], v227 offset:0x6800
	ds_read_b64_tr_b16 v[206:207], v227 offset:0x7000
	ds_read_b64_tr_b16 v[208:209], v227 offset:0x7800
	s_waitcnt lgkmcnt(0)
	s_add_i32 s4, s68, 64
	s_add_i32 s69, s68, 1
	v_mfma_f32_32x32x16_bf16 v[64:79], v[180:183], v[202:205], v[64:79]
	v_mfma_f32_32x32x16_bf16 v[64:79], v[184:187], v[196:199], v[64:79]
	ds_read_b64_tr_b16 v[196:197], v227 offset:0x4200
	ds_read_b64_tr_b16 v[198:199], v227 offset:0x4a00
	ds_read_b64_tr_b16 v[202:203], v227 offset:0x5200
	ds_read_b64_tr_b16 v[204:205], v227 offset:0x5a00
	v_mfma_f32_32x32x16_bf16 v[64:79], v[188:191], v[210:213], v[64:79]
	v_mfma_f32_32x32x16_bf16 v[64:79], v[192:195], v[206:209], v[64:79]
	ds_read_b64_tr_b16 v[206:207], v227 offset:0x6200
	ds_read_b64_tr_b16 v[208:209], v227 offset:0x6a00
	ds_read_b64_tr_b16 v[210:211], v227 offset:0x7200
	ds_read_b64_tr_b16 v[212:213], v227 offset:0x7a00
	s_waitcnt lgkmcnt(0)
	v_mfma_f32_32x32x16_bf16 v[48:63], v[180:183], v[196:199], v[48:63]
	ds_read_b64_tr_b16 v[196:197], v227 offset:0x4400
	ds_read_b64_tr_b16 v[198:199], v227 offset:0x4c00
	v_mfma_f32_32x32x16_bf16 v[48:63], v[184:187], v[202:205], v[48:63]
	ds_read_b64_tr_b16 v[202:203], v227 offset:0x5400
	ds_read_b64_tr_b16 v[204:205], v227 offset:0x5c00
	v_mfma_f32_32x32x16_bf16 v[48:63], v[188:191], v[206:209], v[48:63]
	ds_read_b64_tr_b16 v[206:207], v227 offset:0x6400
	ds_read_b64_tr_b16 v[208:209], v227 offset:0x6c00
	v_mfma_f32_32x32x16_bf16 v[48:63], v[192:195], v[210:213], v[48:63]
	ds_read_b64_tr_b16 v[210:211], v227 offset:0x7400
	ds_read_b64_tr_b16 v[212:213], v227 offset:0x7c00
	s_waitcnt lgkmcnt(0)
	v_mfma_f32_32x32x16_bf16 v[32:47], v[180:183], v[196:199], v[32:47]
	ds_read_b64_tr_b16 v[196:197], v227 offset:0x4600
	ds_read_b64_tr_b16 v[198:199], v227 offset:0x4e00
	v_mfma_f32_32x32x16_bf16 v[32:47], v[184:187], v[202:205], v[32:47]
	ds_read_b64_tr_b16 v[202:203], v227 offset:0x5600
	ds_read_b64_tr_b16 v[204:205], v227 offset:0x5e00
	v_mfma_f32_32x32x16_bf16 v[32:47], v[188:191], v[206:209], v[32:47]
	ds_read_b64_tr_b16 v[206:207], v227 offset:0x6600
	ds_read_b64_tr_b16 v[208:209], v227 offset:0x6e00
	v_mfma_f32_32x32x16_bf16 v[32:47], v[192:195], v[210:213], v[32:47]
	ds_read_b64_tr_b16 v[210:211], v227 offset:0x7600
	ds_read_b64_tr_b16 v[212:213], v227 offset:0x7e00
	s_waitcnt lgkmcnt(0)
	v_mfma_f32_32x32x16_bf16 v[16:31], v[180:183], v[196:199], v[16:31]
	s_cmp_le_i32 s4, s57
	s_cselect_b64 s[4:5], -1, 0
	s_cmp_gt_i32 s69, s58
	s_cselect_b64 s[72:73], -1, 0
	s_and_b64 s[4:5], s[4:5], s[72:73]
	s_and_b64 vcc, exec, s[4:5]
	v_mfma_f32_32x32x16_bf16 v[16:31], v[184:187], v[202:205], v[16:31]
	v_mfma_f32_32x32x16_bf16 v[16:31], v[188:191], v[206:209], v[16:31]
	v_mfma_f32_32x32x16_bf16 v[16:31], v[192:195], v[210:213], v[16:31]
	s_cbranch_vccnz .LBB0_1257
	v_add_u32_e32 v0, 0x103b, v243
	v_cmp_gt_u32_e32 vcc, s81, v0
	v_add_u32_e32 v0, 27, v243
	s_nop 0
	v_cndmask_b32_e32 v128, v200, v128, vcc
	v_cmp_lt_u32_e32 vcc, s82, v0
	v_add_u32_e32 v0, 58, v243
	s_nop 0
	v_cndmask_b32_e32 v112, v200, v112, vcc
	v_cmp_lt_u32_e32 vcc, s82, v0
	v_add_u32_e32 v0, 26, v243
	s_nop 0
	v_cndmask_b32_e32 v129, v200, v129, vcc
	v_cmp_lt_u32_e32 vcc, s82, v0
	v_add_u32_e32 v0, 57, v243
	s_nop 0
	v_cndmask_b32_e32 v113, v200, v113, vcc
	v_cmp_lt_u32_e32 vcc, s82, v0
	v_add_u32_e32 v0, 25, v243
	s_nop 0
	v_cndmask_b32_e32 v130, v200, v130, vcc
	v_cmp_lt_u32_e32 vcc, s82, v0
	v_add_u32_e32 v0, 56, v243
	s_nop 0
	v_cndmask_b32_e32 v114, v200, v114, vcc
	v_cmp_lt_u32_e32 vcc, s82, v0
	v_add_u32_e32 v0, 24, v243
	s_nop 0
	v_cndmask_b32_e32 v131, v200, v131, vcc
	v_cmp_lt_u32_e32 vcc, s82, v0
	v_add_u32_e32 v0, 51, v243
	s_nop 0
	v_cndmask_b32_e32 v115, v200, v115, vcc
	v_cmp_lt_u32_e32 vcc, s82, v0
	v_add_u32_e32 v0, 19, v243
	s_nop 0
	v_cndmask_b32_e32 v132, v200, v132, vcc
	v_cmp_lt_u32_e32 vcc, s82, v0
	v_add_u32_e32 v0, 50, v243
	s_nop 0
	v_cndmask_b32_e32 v116, v200, v116, vcc
	v_cmp_lt_u32_e32 vcc, s82, v0
	v_add_u32_e32 v0, 18, v243
	s_nop 0
	v_cndmask_b32_e32 v133, v200, v133, vcc
	v_cmp_lt_u32_e32 vcc, s82, v0
	v_add_u32_e32 v0, 49, v243
	s_nop 0
	v_cndmask_b32_e32 v117, v200, v117, vcc
	v_cmp_lt_u32_e32 vcc, s82, v0
	v_add_u32_e32 v0, 17, v243
	s_nop 0
	v_cndmask_b32_e32 v134, v200, v134, vcc
	v_cmp_lt_u32_e32 vcc, s82, v0
	v_add_u32_e32 v0, 48, v243
	s_nop 0
	v_cndmask_b32_e32 v118, v200, v118, vcc
	v_cmp_lt_u32_e32 vcc, s82, v0
	v_add_u32_e32 v0, 16, v243
	s_nop 0
	v_cndmask_b32_e32 v135, v200, v135, vcc
	v_cmp_lt_u32_e32 vcc, s82, v0
	v_add_u32_e32 v0, 43, v243
	s_nop 0
	v_cndmask_b32_e32 v119, v200, v119, vcc
	v_cmp_lt_u32_e32 vcc, s82, v0
	v_add_u32_e32 v0, 11, v243
	s_nop 0
	v_cndmask_b32_e32 v136, v200, v136, vcc
	v_cmp_lt_u32_e32 vcc, s82, v0
	v_add_u32_e32 v0, 42, v243
	s_nop 0
	v_cndmask_b32_e32 v120, v200, v120, vcc
	v_cmp_lt_u32_e32 vcc, s82, v0
	v_add_u32_e32 v0, 10, v243
	s_nop 0
	v_cndmask_b32_e32 v137, v200, v137, vcc
	v_cmp_lt_u32_e32 vcc, s82, v0
	v_add_u32_e32 v0, 41, v243
	s_nop 0
	v_cndmask_b32_e32 v121, v200, v121, vcc
	v_cmp_lt_u32_e32 vcc, s82, v0
	v_add_u32_e32 v0, 9, v243
	s_nop 0
	v_cndmask_b32_e32 v138, v200, v138, vcc
	v_cmp_lt_u32_e32 vcc, s82, v0
	v_add_u32_e32 v0, 40, v243
	s_nop 0
	v_cndmask_b32_e32 v122, v200, v122, vcc
	v_cmp_lt_u32_e32 vcc, s82, v0
	v_add_u32_e32 v0, 8, v243
	s_nop 0
	v_cndmask_b32_e32 v139, v200, v139, vcc
	v_cmp_lt_u32_e32 vcc, s82, v0
	v_add_u32_e32 v0, 35, v243
	s_nop 0
	v_cndmask_b32_e32 v123, v200, v123, vcc
	v_cmp_lt_u32_e32 vcc, s82, v0
	v_add_u32_e32 v0, 3, v243
	s_nop 0
	v_cndmask_b32_e32 v140, v200, v140, vcc
	v_cmp_lt_u32_e32 vcc, s82, v0
	v_add_u32_e32 v0, 34, v243
	s_nop 0
	v_cndmask_b32_e32 v124, v200, v124, vcc
	v_cmp_lt_u32_e32 vcc, s82, v0
	v_add_u32_e32 v0, 2, v243
	s_nop 0
	v_cndmask_b32_e32 v141, v200, v141, vcc
	v_cmp_lt_u32_e32 vcc, s82, v0
	v_add_u32_e32 v0, 33, v243
	s_nop 0
	v_cndmask_b32_e32 v125, v200, v125, vcc
	v_cmp_lt_u32_e32 vcc, s82, v0
	v_add_u32_e32 v0, 1, v243
	s_nop 0
	v_cndmask_b32_e32 v142, v200, v142, vcc
	v_cmp_lt_u32_e32 vcc, s82, v0
	v_add_u32_e32 v0, 32, v243
	s_nop 0
	v_cndmask_b32_e32 v126, v200, v126, vcc
	v_cmp_lt_u32_e32 vcc, s82, v0
	s_nop 1
	v_cndmask_b32_e32 v143, v200, v143, vcc
	v_cmp_lt_u32_e32 vcc, s82, v243
	s_nop 1
	v_cndmask_b32_e32 v127, v200, v127, vcc

; #define SBAR() __builtin_amdgcn_sched_barrier(0)
; #define SLOAD_H(Kp, Vp, Cp, k0) do { S.st_b0 = (Cp)[(unsigned)((k0) + sr + 32 * (tid & 1))]; S.st_v0 = load8<TIn>(ROW(Vp, k0, sr)); S.st_v1 = load8<TIn>(ROW(Vp, k0, 32 + sr));              \
;                          S.st_k0 = load8<TIn>(ROW(Kp, k0, sr)); S.st_k1 = load8<TIn>(ROW(Kp, k0, 32 + sr)); } while (0)
; #define SLOAD_F(p, k0) do { S.sf0 = *(const f32x4*)ROW(p, k0, sr); S.sf1 = *(const f32x4*)(ROW(p, k0, sr) + 4);                \
;                             S.sf2 = *(const f32x4*)ROW(p, k0, 32 + sr); S.sf3 = *(const f32x4*)(ROW(p, k0, 32 + sr) + 4); } while (0)
; #define ACT(t) (KBASE(t) <= qlo + QBLK - 1 && KBASE(t) + KVBLK - 1 >= qlo - W + 1)
; __device__ __forceinline__ void finishSM(f32x16& p0, f32x16& p1, float alpha, float& l_reg, bf16x8& pa0, bf16x8& pa1, bf16x8& pa2, bf16x8& pa3) {
;     for (int r = 0; r < 16; ++r) p1[r] = __builtin_amdgcn_exp2f(p1[r]);
;     float ps = 0; for (int r = 0; r < 16; ++r) ps += p0[r]; for (int r = 0; r < 16; ++r) ps += p1[r];
;     { auto rr = __builtin_amdgcn_permlane32_swap(__float_as_uint(ps), __float_as_uint(ps), false, false);
;       ps = __uint_as_float(rr[0]) + __uint_as_float(rr[1]); }
;     l_reg = l_reg * alpha + ps;
;     ...
;     PK4(p0, 0, pa0); PK4(p0, 8, pa1); PK4(p1, 0, pa2); PK4(p1, 8, pa3);
; template <class TIn, class TOut>
; __device__ __forceinline__ void causal_swa_block(const BlockRef<TIn, TOut>& cur, const BlockRef<TIn, TOut>& nxt, int skv, int W, char* lds, Seam<TIn>& S) {
;     ...
;     if constexpr (F32) { SLOAD_F((const float*)nxt.K, kbn); SBAR();
; #pragma unroll
;         for (int e = 0; e < 8; ++e) S.tq[e] = *(const f32x4*)QROW(e); }
;     else { SLOAD_H(nxt.K, nxt.V, nxt.CB, kbn); SBAR();
; #pragma unroll
;         for (int d0 = 0; d0 < 8; ++d0) S.qr[d0] = load8<TIn>(nxt.Q + (unsigned)((wid * QBLK + r32) * PITCH + d0 * 16 + hi * 8)); }
;     SBAR();
;     finishSM(pA0, pA1, alA, l_reg, pa0, pa1, pa2, pa3); SBAR();
;     if constexpr (F32) {
; #pragma unroll
;         for (int e = 8; e < 16; ++e) S.tq[e] = *(const f32x4*)QROW(e); SBAR(); }
;     ...
;     pv_tile<0, SK>(o, vb0, pa0, pa1, pa2, pa3, ACT(even ? NT - 2 : NT - 1));
.LBB0_1265:
	s_add_i32 s4, s53, 0xfffff001
	s_and_b32 s4, s4, 0xffffff00
	s_cmpk_gt_i32 s53, 0xfff
	s_cselect_b32 s4, s4, 0
	v_add_u32_e32 v4, s4, v230
	v_add_u32_e32 v0, v4, v219
	v_lshl_add_u64 v[2:3], v[0:1], 2, s[24:25]
	v_lshl_or_b32 v0, v4, 11, v229
	global_load_dword v176, v[2:3], off
	v_lshlrev_b64 v[2:3], 1, v[0:1]
	v_add_u32_e32 v0, s4, v231
	v_lshl_or_b32 v0, v0, 11, v229
	v_lshl_add_u64 v[4:5], s[18:19], 0, v[2:3]
	v_lshlrev_b64 v[6:7], 1, v[0:1]
	v_lshl_add_u64 v[2:3], s[26:27], 0, v[2:3]
	v_lshl_add_u64 v[8:9], s[18:19], 0, v[6:7]
	global_load_dwordx4 v[124:127], v[4:5], off
	global_load_dwordx4 v[112:115], v[8:9], off
	v_lshl_add_u64 v[4:5], s[26:27], 0, v[6:7]
	global_load_dwordx4 v[116:119], v[2:3], off
	global_load_dwordx4 v[120:123], v[4:5], off
	v_or_b32_e32 v0, s60, v220
	v_lshlrev_b32_e32 v2, 3, v221
	v_lshl_or_b32 v0, v0, 11, v2
	v_lshl_add_u64 v[2:3], v[0:1], 1, s[14:15]
	global_load_dwordx4 v[172:175], v[2:3], off
	global_load_dwordx4 v[168:171], v[2:3], off offset:32
	global_load_dwordx4 v[164:167], v[2:3], off offset:64
	global_load_dwordx4 v[160:163], v[2:3], off offset:96
	global_load_dwordx4 v[156:159], v[2:3], off offset:128
	global_load_dwordx4 v[152:155], v[2:3], off offset:160
	global_load_dwordx4 v[148:151], v[2:3], off offset:192
	global_load_dwordx4 v[144:147], v[2:3], off offset:224
	v_add_f32_e32 v0, 0, v191
	v_add_f32_e32 v0, v193, v0
	v_add_f32_e32 v0, v189, v0
	v_add_f32_e32 v0, v192, v0
	v_add_f32_e32 v0, v188, v0
	v_add_f32_e32 v0, v190, v0
	v_add_f32_e32 v0, v186, v0
	v_add_f32_e32 v0, v187, v0
	v_add_f32_e32 v0, v182, v0
	v_add_f32_e32 v0, v185, v0
	v_add_f32_e32 v0, v179, v0
	v_add_f32_e32 v0, v183, v0
	v_exp_f32_e32 v10, v142
	v_add_f32_e32 v0, v177, v0
	v_exp_f32_e32 v11, v143
	v_add_f32_e32 v0, v184, v0
	v_exp_f32_e32 v12, v140
	v_add_f32_e32 v0, v178, v0
	v_exp_f32_e32 v13, v141
	v_add_f32_e32 v0, v181, v0
	v_exp_f32_e32 v14, v138
	v_add_f32_e32 v0, v10, v0
	v_exp_f32_e32 v15, v139
	v_add_f32_e32 v0, v11, v0
	v_exp_f32_e32 v136, v136
	v_add_f32_e32 v0, v12, v0
	v_exp_f32_e32 v137, v137
	v_add_f32_e32 v0, v13, v0
	v_exp_f32_e32 v134, v134
	v_add_f32_e32 v0, v14, v0
	v_exp_f32_e32 v135, v135
	v_add_f32_e32 v0, v15, v0
	v_exp_f32_e32 v132, v132
	v_add_f32_e32 v0, v136, v0
	v_exp_f32_e32 v133, v133
	v_add_f32_e32 v0, v137, v0
	v_exp_f32_e32 v130, v130
	v_add_f32_e32 v0, v134, v0
	v_exp_f32_e32 v131, v131
	v_add_f32_e32 v0, v135, v0
	v_exp_f32_e32 v138, v128
	v_add_f32_e32 v0, v132, v0
	v_exp_f32_e32 v139, v129
	v_add_f32_e32 v0, v133, v0
	v_add_f32_e32 v0, v130, v0
	v_add_f32_e32 v0, v131, v0
	v_add_f32_e32 v0, v138, v0
	v_add_f32_e32 v0, v139, v0
	v_mov_b32_e32 v2, v0
	s_nop 1
	v_permlane32_swap_b32_e32 v0, v2
	v_add_f32_e32 v0, v0, v2
	v_fmac_f32_e32 v0, v241, v240
	v_cvt_pk_bf16_f32 v2, v191, v193
	v_cvt_pk_bf16_f32 v3, v189, v192
	v_cvt_pk_bf16_f32 v4, v188, v190
	v_cvt_pk_bf16_f32 v5, v186, v187
	v_cvt_pk_bf16_f32 v6, v182, v185
	v_cvt_pk_bf16_f32 v7, v179, v183
	v_cvt_pk_bf16_f32 v8, v177, v184
	v_cvt_pk_bf16_f32 v9, v178, v181
	v_cvt_pk_bf16_f32 v10, v10, v11
	v_cvt_pk_bf16_f32 v11, v12, v13
	v_cvt_pk_bf16_f32 v12, v14, v15
	v_cvt_pk_bf16_f32 v13, v136, v137
	v_cvt_pk_bf16_f32 v128, v134, v135
	v_cvt_pk_bf16_f32 v129, v132, v133
	v_cvt_pk_bf16_f32 v130, v130, v131
	v_cvt_pk_bf16_f32 v131, v138, v139
	s_nop 0
	v_permlane32_swap_b32_e32 v2, v4
	v_permlane32_swap_b32_e32 v3, v5
	v_permlane32_swap_b32_e32 v6, v8
	v_permlane32_swap_b32_e32 v7, v9
	v_permlane32_swap_b32_e32 v10, v12
	v_permlane32_swap_b32_e32 v11, v13
	v_permlane32_swap_b32_e32 v128, v130
	v_permlane32_swap_b32_e32 v129, v131
	ds_read_b64_tr_b16 v[132:133], v227 offset:0
	ds_read_b64_tr_b16 v[134:135], v227 offset:0x800
	ds_read_b64_tr_b16 v[136:137], v227 offset:0x1000
	ds_read_b64_tr_b16 v[138:139], v227 offset:0x1800
	ds_read_b64_tr_b16 v[140:141], v227 offset:0x2000
	ds_read_b64_tr_b16 v[142:143], v227 offset:0x2800
	ds_read_b64_tr_b16 v[182:183], v227 offset:0x3000
	ds_read_b64_tr_b16 v[184:185], v227 offset:0x3800
	s_waitcnt lgkmcnt(0)
	s_nop 0
	v_mfma_f32_32x32x16_bf16 v[64:79], v[2:5], v[132:135], v[64:79]
	ds_read_b64_tr_b16 v[132:133], v227 offset:0x200
	ds_read_b64_tr_b16 v[134:135], v227 offset:0xa00
	v_mfma_f32_32x32x16_bf16 v[64:79], v[6:9], v[136:139], v[64:79]
	ds_read_b64_tr_b16 v[136:137], v227 offset:0x1200
	ds_read_b64_tr_b16 v[138:139], v227 offset:0x1a00
	v_mfma_f32_32x32x16_bf16 v[64:79], v[10:13], v[140:143], v[64:79]
	ds_read_b64_tr_b16 v[140:141], v227 offset:0x2200
	ds_read_b64_tr_b16 v[142:143], v227 offset:0x2a00
	v_mfma_f32_32x32x16_bf16 v[64:79], v[128:131], v[182:185], v[64:79]
	ds_read_b64_tr_b16 v[182:183], v227 offset:0x3200
	ds_read_b64_tr_b16 v[184:185], v227 offset:0x3a00
	s_waitcnt lgkmcnt(0)
	v_mfma_f32_32x32x16_bf16 v[48:63], v[2:5], v[132:135], v[48:63]
	ds_read_b64_tr_b16 v[132:133], v227 offset:0x400
	ds_read_b64_tr_b16 v[134:135], v227 offset:0xc00
	v_mfma_f32_32x32x16_bf16 v[48:63], v[6:9], v[136:139], v[48:63]
	ds_read_b64_tr_b16 v[136:137], v227 offset:0x1400
	ds_read_b64_tr_b16 v[138:139], v227 offset:0x1c00
	v_mfma_f32_32x32x16_bf16 v[48:63], v[10:13], v[140:143], v[48:63]
	ds_read_b64_tr_b16 v[140:141], v227 offset:0x2400
	ds_read_b64_tr_b16 v[142:143], v227 offset:0x2c00
	v_mfma_f32_32x32x16_bf16 v[48:63], v[128:131], v[182:185], v[48:63]
	ds_read_b64_tr_b16 v[182:183], v227 offset:0x3400
	ds_read_b64_tr_b16 v[184:185], v227 offset:0x3c00
	s_waitcnt lgkmcnt(0)
	v_mfma_f32_32x32x16_bf16 v[32:47], v[2:5], v[132:135], v[32:47]
	ds_read_b64_tr_b16 v[132:133], v227 offset:0x600
	ds_read_b64_tr_b16 v[134:135], v227 offset:0xe00
	v_mfma_f32_32x32x16_bf16 v[32:47], v[6:9], v[136:139], v[32:47]
	ds_read_b64_tr_b16 v[136:137], v227 offset:0x1600
	ds_read_b64_tr_b16 v[138:139], v227 offset:0x1e00
	v_mfma_f32_32x32x16_bf16 v[32:47], v[10:13], v[140:143], v[32:47]
	ds_read_b64_tr_b16 v[140:141], v227 offset:0x2600
	ds_read_b64_tr_b16 v[142:143], v227 offset:0x2e00
	v_mfma_f32_32x32x16_bf16 v[32:47], v[128:131], v[182:185], v[32:47]
	ds_read_b64_tr_b16 v[182:183], v227 offset:0x3600
	ds_read_b64_tr_b16 v[184:185], v227 offset:0x3e00
	s_waitcnt lgkmcnt(0)
	v_mfma_f32_32x32x16_bf16 v[16:31], v[2:5], v[132:135], v[16:31]
	s_andn2_b64 vcc, exec, s[2:3]
	v_mfma_f32_32x32x16_bf16 v[16:31], v[6:9], v[136:139], v[16:31]
	v_mfma_f32_32x32x16_bf16 v[16:31], v[10:13], v[140:143], v[16:31]
	v_mfma_f32_32x32x16_bf16 v[16:31], v[128:131], v[182:185], v[16:31]
	s_cbranch_vccnz .LBB0_1273
; #define SBAR() __builtin_amdgcn_sched_barrier(0)
; #define RESC(a) do { if (__any((a) < 1.f)) { if (hi == 0) al_l[r32] = (a); asm volatile("s_waitcnt lgkmcnt(0)" ::: "memory");              \
;                      for (int d_ = 0; d_ < 4; ++d_) for (int r = 0; r < 16; ++r) o[d_][r] *= al_l[crow(r, hi)]; } } while (0)
; #define ACT(t) (KBASE(t) <= qlo + QBLK - 1 && KBASE(t) + KVBLK - 1 >= qlo - W + 1)
; #define MASKT(P0_, P1_, t) do { const int kb_ = KBASE(t); if ((!SK || ACT(t)) && (kb_ + KVBLK - 1 > qlo || kb_ <= qlo + QBLK - 1 - W)) mask_tile(P0_, P1_, qm - kb_, (unsigned)W); } while (0)
; __device__ __forceinline__ void mask_tile(f32x16& p0, f32x16& p1, int dq, unsigned W) {
;     const float NEG = -__builtin_inff();
; #pragma unroll
;     for (int r = 0; r < 16; ++r) {
;         const int c = (r & 3) + 8 * (r >> 2);
;         if ((unsigned)(dq - c) >= W) p0[r] = NEG;
;         if ((unsigned)(dq - c - 32) >= W) p1[r] = NEG;
;     }
; }
; template <class TIn, class TOut>
; __device__ __forceinline__ void causal_swa_block(const BlockRef<TIn, TOut>& cur, const BlockRef<TIn, TOut>& nxt, int skv, int W, char* lds, Seam<TIn>& S) {
;     ...
;     if (even) { MASKT(pB0, pB1, NT - 1); partialSM(pB0, pB1, m_reg, mnB, alB); __syncthreads(); RESC(alB);
;         finishSM(pB0, pB1, alB, l_reg, pa0, pa1, pa2, pa3); SBAR(); pv_tile<1, SK>(o, vb0, pa0, pa1, pa2, pa3, ACT(NT - 1)); }
	s_lshl_b32 s3, s56, 6
	s_sub_i32 s2, s3, 64
	s_add_i32 s3, s3, -1
	s_cmp_le_i32 s3, s57
	s_cselect_b64 s[4:5], -1, 0
	s_cmp_gt_i32 s2, s58
	s_cselect_b64 s[28:29], -1, 0
	s_and_b64 s[4:5], s[4:5], s[28:29]
	s_and_b64 vcc, exec, s[4:5]
	v_mov_b32_e32 v234, v228
	s_cbranch_vccnz .LBB0_1268
	v_subrev_u32_e32 v2, s2, v201
	v_cmp_gt_u32_e32 vcc, s81, v2
	v_add_u32_e32 v3, 0xffffefe0, v2
	s_nop 0
	v_cndmask_b32_e32 v80, v200, v80, vcc
	v_cmp_lt_u32_e32 vcc, s82, v3
	v_add_u32_e32 v3, 0xffffefff, v2
	s_nop 0
	v_cndmask_b32_e32 v96, v200, v96, vcc
	v_cmp_lt_u32_e32 vcc, s82, v3
	v_add_u32_e32 v3, 0xffffefdf, v2
	s_nop 0
	v_cndmask_b32_e32 v81, v200, v81, vcc
	v_cmp_lt_u32_e32 vcc, s82, v3
	v_add_u32_e32 v3, 0xffffeffe, v2
	s_nop 0
	v_cndmask_b32_e32 v97, v200, v97, vcc
	v_cmp_lt_u32_e32 vcc, s82, v3
	v_add_u32_e32 v3, 0xffffefde, v2
	s_nop 0
	v_cndmask_b32_e32 v82, v200, v82, vcc
	v_cmp_lt_u32_e32 vcc, s82, v3
	v_add_u32_e32 v3, 0xffffeffd, v2
	s_nop 0
	v_cndmask_b32_e32 v98, v200, v98, vcc
	v_cmp_lt_u32_e32 vcc, s82, v3
	v_add_u32_e32 v3, 0xffffefdd, v2
	s_nop 0
	v_cndmask_b32_e32 v83, v200, v83, vcc
	v_cmp_lt_u32_e32 vcc, s82, v3
	v_add_u32_e32 v3, 0xffffeff8, v2
	s_nop 0
	v_cndmask_b32_e32 v99, v200, v99, vcc
	v_cmp_lt_u32_e32 vcc, s82, v3
	v_add_u32_e32 v3, 0xffffefd8, v2
	s_nop 0
	v_cndmask_b32_e32 v84, v200, v84, vcc
	v_cmp_lt_u32_e32 vcc, s82, v3
	v_add_u32_e32 v3, 0xffffeff7, v2
	s_nop 0
	v_cndmask_b32_e32 v100, v200, v100, vcc
	v_cmp_lt_u32_e32 vcc, s82, v3
	v_add_u32_e32 v3, 0xffffefd7, v2
	s_nop 0
	v_cndmask_b32_e32 v85, v200, v85, vcc
	v_cmp_lt_u32_e32 vcc, s82, v3
	v_add_u32_e32 v3, 0xffffeff6, v2
	s_nop 0
	v_cndmask_b32_e32 v101, v200, v101, vcc
	v_cmp_lt_u32_e32 vcc, s82, v3
	v_add_u32_e32 v3, 0xffffefd6, v2
	s_nop 0
	v_cndmask_b32_e32 v86, v200, v86, vcc
	v_cmp_lt_u32_e32 vcc, s82, v3
	v_add_u32_e32 v3, 0xffffeff5, v2
	s_nop 0
	v_cndmask_b32_e32 v102, v200, v102, vcc
	v_cmp_lt_u32_e32 vcc, s82, v3
	v_add_u32_e32 v3, 0xffffefd5, v2
	s_nop 0
	v_cndmask_b32_e32 v87, v200, v87, vcc
	v_cmp_lt_u32_e32 vcc, s82, v3
	v_add_u32_e32 v3, 0xffffeff0, v2
	s_nop 0
	v_cndmask_b32_e32 v103, v200, v103, vcc
	v_cmp_lt_u32_e32 vcc, s82, v3
	v_add_u32_e32 v3, 0xffffefd0, v2
	s_nop 0
	v_cndmask_b32_e32 v88, v200, v88, vcc
	v_cmp_lt_u32_e32 vcc, s82, v3
	v_add_u32_e32 v3, 0xffffefef, v2
	s_nop 0
	v_cndmask_b32_e32 v104, v200, v104, vcc
	v_cmp_lt_u32_e32 vcc, s82, v3
	v_add_u32_e32 v3, 0xffffefcf, v2
	s_nop 0
	v_cndmask_b32_e32 v89, v200, v89, vcc
	v_cmp_lt_u32_e32 vcc, s82, v3
	v_add_u32_e32 v3, 0xffffefee, v2
	s_nop 0
	v_cndmask_b32_e32 v105, v200, v105, vcc
	v_cmp_lt_u32_e32 vcc, s82, v3
	v_add_u32_e32 v3, 0xffffefce, v2
	s_nop 0
	v_cndmask_b32_e32 v90, v200, v90, vcc
	v_cmp_lt_u32_e32 vcc, s82, v3
	v_add_u32_e32 v3, 0xffffefed, v2
	s_nop 0
	v_cndmask_b32_e32 v106, v200, v106, vcc
	v_cmp_lt_u32_e32 vcc, s82, v3
	v_add_u32_e32 v3, 0xffffefcd, v2
	s_nop 0
	v_cndmask_b32_e32 v91, v200, v91, vcc
	v_cmp_lt_u32_e32 vcc, s82, v3
	v_add_u32_e32 v3, 0xffffefe8, v2
	s_nop 0
	v_cndmask_b32_e32 v107, v200, v107, vcc
	v_cmp_lt_u32_e32 vcc, s82, v3
	v_add_u32_e32 v3, 0xffffefc8, v2
	s_nop 0
	v_cndmask_b32_e32 v92, v200, v92, vcc
	v_cmp_lt_u32_e32 vcc, s82, v3
	v_add_u32_e32 v3, 0xffffefe7, v2
	s_nop 0
	v_cndmask_b32_e32 v108, v200, v108, vcc
	v_cmp_lt_u32_e32 vcc, s82, v3
	v_add_u32_e32 v3, 0xffffefc7, v2
	s_nop 0
	v_cndmask_b32_e32 v93, v200, v93, vcc
	v_cmp_lt_u32_e32 vcc, s82, v3
	v_add_u32_e32 v3, 0xffffefe6, v2
	s_nop 0
	v_cndmask_b32_e32 v109, v200, v109, vcc
	v_cmp_lt_u32_e32 vcc, s82, v3
	v_add_u32_e32 v3, 0xffffefc6, v2
	s_nop 0
	v_cndmask_b32_e32 v94, v200, v94, vcc
	v_cmp_lt_u32_e32 vcc, s82, v3
	v_add_u32_e32 v3, 0xffffefe5, v2
	v_add_u32_e32 v2, 0xffffefc5, v2
	v_cndmask_b32_e32 v110, v200, v110, vcc
	v_cmp_lt_u32_e32 vcc, s82, v3
	s_nop 1
	v_cndmask_b32_e32 v95, v200, v95, vcc
	v_cmp_lt_u32_e32 vcc, s82, v2
	s_nop 1
	v_cndmask_b32_e32 v111, v200, v111, vcc

; __device__ __forceinline__ void sample_attn(const Args& a, int j, int bh, unsigned char* ldsb, bool dummy = false) {
;     constexpr int PP = 136;
;     float* wmx = (float*)ldsb;
;     bf16_t* Pb = (bf16_t*)(ldsb + 1024);
;     float* lfin = (float*)(ldsb + 1024 + 2 * 16 * PP * 2);
;     const int tid = otid(), lane = tid & 63, wid = __builtin_amdgcn_readfirstlane(tid >> 6), fr = lane & 15, fq = lane >> 4, b = bh >> 4, h = bh & 15;
;     const bf16_t* Qb = (const bf16_t*)(a.p->ws + WS_R0); const bf16_t* ZS = (const bf16_t*)(a.p->ws + WS_R0 + 3 * RSZ); bf16_t* O = (bf16_t*)(a.p->ws + (dummy ? WS_DUMMY : WS_R0));
;     const float* ck = a.p->in[2] + (size_t)(j * 8 + b) * PAST * EB + h * 128; const float* cv = a.p->in[3] + (size_t)(j * 8 + b) * PAST * EB + h * 128;
;     const float* nk = a.p->out + O_FKS + ((size_t)j * MS + b * TS) * EB + h * 128; const float* nv = a.p->out + O_FVS + ((size_t)j * MS + b * TS) * EB + h * 128;
;     const float* cb = (const float*)(a.p->ws + WS_CBS) + (size_t)bh * SKS;
;     ...
;     __syncthreads();
;     if (mode != 1) for (int bh = (int)gridDim.x - 1 - (int)blockIdx.x; bh < NBH; bh += gridDim.x) sample_attn(a, j, bh, ldsb, mode == 2);
.LBB0_1413:
	v_mov_b32_e32 v200, 64
	v_xor_b32_e32 v201, 8, v253
	v_xor_b32_e32 v214, 1, v253
	v_xor_b32_e32 v215, 4, v253
	v_mov_b32_e32 v216, 0xff800000
	v_readlane_b32 s2, v254, 19
	v_readlane_b32 s3, v254, 20
	s_andn2_b64 vcc, exec, s[2:3]
	s_barrier
	s_cbranch_vccnz .LBB0_1463
	s_lshl_b32 s0, s62, 18
	s_add_u32 s34, s6, 0xee80000
	s_addc_u32 s35, s7, 0
	v_readlane_b32 s36, v254, 56
	v_readlane_b32 s37, v254, 55
	s_branch .LBB0_1416
